# v_c7 + back-edge rotation in all five GEMM K-loops: loop-carried scalar block and exit test moved from after the loop-back barrier / loop head into the last MFMA run's shadow
# baseline (speedup 1.0000x reference)
; #define PG8_STAGE(bufoff, gbase, voff) do { _Pragma("unroll") for (int _i = 0; _i < 2; ++_i) \
;         __builtin_amdgcn_global_load_lds((const unsigned*)((const char*)(gbase) + (voff)[_i]), (PG8_LAS unsigned*)(lds + (bufoff) + ldsw + _i * 8192), 16, 0, 0); } while (0)
; #define PG8_LDA(dst, b, h) do { _Pragma("unroll") for (int m = 0; m < 4; ++m) _Pragma("unroll") for (int k = 0; k < 2; ++k) dst[m][k] = *(const PG8_LAS bf16x8*)(lds + PG8_SA(b, h) + aoff + m * 2048 + k * 1024); } while (0)
; #define PG8_LDB(dst, b, h) do { _Pragma("unroll") for (int n = 0; n < 2; ++n) _Pragma("unroll") for (int k = 0; k < 2; ++k) dst[n][k] = *(const PG8_LAS bf16x8*)(lds + PG8_SB(b, h) + boff + n * 2048 + k * 1024); } while (0)
; #define PG8_SCHED __builtin_amdgcn_sched_barrier(0)
; template <class Epi, class Sched, bool ALIGN_EPI = false, bool SP2 = false, bool F16 = false>
; __device__ __forceinline__ void gemm_phase(PG8_LAS unsigned char* lds, const Gemm g, const Sched& S, const Epi& E) {
;     ...
;     f32x4 acc[2][2][4][2];
; #pragma unroll
;     for (int a = 0; a < 2; ++a)
; #pragma unroll
;         for (int b = 0; b < 2; ++b)
; #pragma unroll
;             for (int m = 0; m < 4; ++m)
; #pragma unroll
;                 for (int n = 0; n < 2; ++n) acc[a][b][m][n] = (f32x4){0.f, 0.f, 0.f, 0.f};
;     ...
;     for (;;) {
;         const bool has_next = S.next(ui + 1, nxt);
;         const char* nA = has_next ? (const char*)g.A + (size_t)nxt.pm * tstep : cA; const char* nB = has_next ? (const char*)g.Bt + (size_t)nxt.pn * tstep : cB;
;         for (int t = 0; t < nt; t += 2) {
;             const bool last = (t == nt - 2);
;             const char* a1 = cA + (size_t)(t + 1) * kstep;
;             const char* a2 = last ? nA : cA + (size_t)(t + 2) * kstep; const char* b2 = last ? nB : cB + (size_t)(t + 2) * kstep;
;             const char* a3 = a2 + kstep; const char* b3 = b2 + kstep;
;             if (last && has_next) S.a_ready(nxt);
;             if constexpr (SP2) {
;             PG8_LDB(B0, 0, 0); PG8_LDB(B1, 0, 1); PG8_SCHED; PG8_LDA(At, 0, 0); PG8_STAGE(PG8_SA(1, 1), a1 + hstep, voffA);
.LBB0_506:
	s_ashr_i32 s21, s20, 31
	s_lshl_b64 s[26:27], s[20:21], 20
	s_add_u32 s26, s48, s26
	s_addc_u32 s27, s49, s27
	s_and_b64 s[40:41], s[38:39], exec
	s_cselect_b32 s21, s27, s43
	s_cselect_b32 s67, s26, s42
	s_ashr_i32 s19, s18, 31
	s_lshl_b64 s[40:41], s[18:19], 20
	s_add_u32 s40, s50, s40
	s_addc_u32 s41, s51, s41
	s_and_b64 s[46:47], s[38:39], exec
	s_cselect_b32 s19, s41, s45
	s_cselect_b32 s68, s40, s44
	s_add_u32 s42, s42, 0x80080
	s_addc_u32 s43, s43, 0
	s_add_u32 s69, s44, 0x100
	v_mov_b32_e32 v2, 0
	s_addc_u32 s70, s45, 0
	s_mov_b32 s71, -2
	v_mov_b32_e32 v3, v2
	v_mov_b32_e32 v4, v2
	v_mov_b32_e32 v5, v2
	v_mov_b32_e32 v6, v2
	v_mov_b32_e32 v7, v2
	v_mov_b32_e32 v8, v2
	v_mov_b32_e32 v9, v2
	v_mov_b32_e32 v10, v2
	v_mov_b32_e32 v11, v2
	v_mov_b32_e32 v12, v2
	v_mov_b32_e32 v13, v2
	v_mov_b32_e32 v14, v2
	v_mov_b32_e32 v15, v2
	v_mov_b32_e32 v16, v2
	v_mov_b32_e32 v17, v2
	v_mov_b32_e32 v26, v2
	v_mov_b32_e32 v27, v2
	v_mov_b32_e32 v28, v2
	v_mov_b32_e32 v29, v2
	v_mov_b32_e32 v30, v2
	v_mov_b32_e32 v31, v2
	v_mov_b32_e32 v32, v2
	v_mov_b32_e32 v33, v2
	v_mov_b32_e32 v42, v2
	v_mov_b32_e32 v43, v2
	v_mov_b32_e32 v44, v2
	v_mov_b32_e32 v45, v2
	v_mov_b32_e32 v46, v2
	v_mov_b32_e32 v47, v2
	v_mov_b32_e32 v48, v2
	v_mov_b32_e32 v49, v2
	v_mov_b32_e32 v18, v2
	v_mov_b32_e32 v19, v2
	v_mov_b32_e32 v20, v2
	v_mov_b32_e32 v21, v2
	v_mov_b32_e32 v22, v2
	v_mov_b32_e32 v23, v2
	v_mov_b32_e32 v24, v2
	v_mov_b32_e32 v25, v2
	v_mov_b32_e32 v34, v2
	v_mov_b32_e32 v35, v2
	v_mov_b32_e32 v36, v2
	v_mov_b32_e32 v37, v2
	v_mov_b32_e32 v38, v2
	v_mov_b32_e32 v39, v2
	v_mov_b32_e32 v40, v2
	v_mov_b32_e32 v41, v2
	v_mov_b32_e32 v50, v2
	v_mov_b32_e32 v51, v2
	v_mov_b32_e32 v52, v2
	v_mov_b32_e32 v53, v2
	v_mov_b32_e32 v54, v2
	v_mov_b32_e32 v55, v2
	v_mov_b32_e32 v56, v2
	v_mov_b32_e32 v57, v2
	v_mov_b32_e32 v58, v2
	v_mov_b32_e32 v59, v2
	v_mov_b32_e32 v60, v2
	v_mov_b32_e32 v61, v2
	v_mov_b32_e32 v62, v2
	v_mov_b32_e32 v63, v2
	v_mov_b32_e32 v64, v2
	v_mov_b32_e32 v65, v2
	v_mov_b32_e32 v66, v2
	v_mov_b32_e32 v67, v2
	v_mov_b32_e32 v68, v2
	v_mov_b32_e32 v69, v2
	v_mov_b32_e32 v70, v2
	v_mov_b32_e32 v71, v2
	v_mov_b32_e32 v72, v2
	v_mov_b32_e32 v73, v2
	v_mov_b32_e32 v74, v2
	v_mov_b32_e32 v75, v2
	v_mov_b32_e32 v76, v2
	v_mov_b32_e32 v77, v2
	v_mov_b32_e32 v78, v2
	v_mov_b32_e32 v79, v2
	v_mov_b32_e32 v80, v2
	v_mov_b32_e32 v81, v2
	v_mov_b32_e32 v90, v2
	v_mov_b32_e32 v91, v2
	v_mov_b32_e32 v92, v2
	v_mov_b32_e32 v93, v2
	v_mov_b32_e32 v94, v2
	v_mov_b32_e32 v95, v2
	v_mov_b32_e32 v96, v2
	v_mov_b32_e32 v97, v2
	v_mov_b32_e32 v106, v2
	v_mov_b32_e32 v107, v2
	v_mov_b32_e32 v108, v2
	v_mov_b32_e32 v109, v2
	v_mov_b32_e32 v110, v2
	v_mov_b32_e32 v111, v2
	v_mov_b32_e32 v112, v2
	v_mov_b32_e32 v113, v2
	v_mov_b32_e32 v82, v2
	v_mov_b32_e32 v83, v2
	v_mov_b32_e32 v84, v2
	v_mov_b32_e32 v85, v2
	v_mov_b32_e32 v86, v2
	v_mov_b32_e32 v87, v2
	v_mov_b32_e32 v88, v2
	v_mov_b32_e32 v89, v2
	v_mov_b32_e32 v98, v2
	v_mov_b32_e32 v99, v2
	v_mov_b32_e32 v100, v2
	v_mov_b32_e32 v101, v2
	v_mov_b32_e32 v102, v2
	v_mov_b32_e32 v103, v2
	v_mov_b32_e32 v104, v2
	v_mov_b32_e32 v105, v2
	v_mov_b32_e32 v114, v2
	v_mov_b32_e32 v115, v2
	v_mov_b32_e32 v116, v2
	v_mov_b32_e32 v117, v2
	v_mov_b32_e32 v118, v2
	v_mov_b32_e32 v119, v2
	v_mov_b32_e32 v120, v2
	v_mov_b32_e32 v121, v2
	v_mov_b32_e32 v122, v2
	v_mov_b32_e32 v123, v2
	v_mov_b32_e32 v124, v2
	v_mov_b32_e32 v125, v2
	v_mov_b32_e32 v126, v2
	v_mov_b32_e32 v127, v2
	v_mov_b32_e32 v128, v2
	v_mov_b32_e32 v129, v2
	s_add_u32 s44, s42, 0xfff80080
	s_addc_u32 s45, s43, -1
	s_add_i32 s72, 0, 0x10000
	s_cmp_eq_u32 s71, 28
	s_cselect_b32 s47, s21, s45
	s_cselect_b32 s46, s67, s44
	s_cselect_b32 s45, s19, s70
	s_cselect_b32 s44, s68, s69
	s_add_i32 s76, 0, 0x14000
.LBB0_507:
	v_add_u32_e32 v158, s72, v143
	v_add_u32_e32 v174, s76, v143
	ds_read_b128 v[146:149], v158
	ds_read_b128 v[150:153], v158 offset:1024
	ds_read_b128 v[154:157], v158 offset:2048
	ds_read_b128 v[158:161], v158 offset:3072
	ds_read_b128 v[162:165], v174
	ds_read_b128 v[166:169], v174 offset:1024
	ds_read_b128 v[170:173], v174 offset:2048
	ds_read_b128 v[174:177], v174 offset:3072
	v_lshl_add_u64 v[210:211], s[42:43], 0, v[136:137]
	s_add_i32 m0, s59, 0xc000
	ds_read_b128 v[178:181], v145
	ds_read_b128 v[182:185], v145 offset:1024
	ds_read_b128 v[186:189], v145 offset:2048
	ds_read_b128 v[190:193], v145 offset:3072
	ds_read_b128 v[194:197], v145 offset:4096
	ds_read_b128 v[198:201], v145 offset:5120
	ds_read_b128 v[202:205], v145 offset:6144
	ds_read_b128 v[206:209], v145 offset:7168
	global_load_lds_dwordx4 v[210:211], off
	v_lshl_add_u64 v[210:211], s[42:43], 0, v[138:139]
	s_add_i32 m0, s59, 0xe000
	s_nop 0
	global_load_lds_dwordx4 v[210:211], off
	s_cmp_eq_u32 s100, 0
	s_cbranch_scc1 .Lur_ip_n0
	s_sub_u32 s100, s100, 1
	s_waitcnt vmcnt(24)
	s_branch .Lur_ip_d0

; #define PG8_STAGE(bufoff, gbase, voff) do { _Pragma("unroll") for (int _i = 0; _i < 2; ++_i) \
;         __builtin_amdgcn_global_load_lds((const unsigned*)((const char*)(gbase) + (voff)[_i]), (PG8_LAS unsigned*)(lds + (bufoff) + ldsw + _i * 8192), 16, 0, 0); } while (0)
; #define PG8_LDA(dst, b, h) do { _Pragma("unroll") for (int m = 0; m < 4; ++m) _Pragma("unroll") for (int k = 0; k < 2; ++k) dst[m][k] = *(const PG8_LAS bf16x8*)(lds + PG8_SA(b, h) + aoff + m * 2048 + k * 1024); } while (0)
; #define PG8_LDB(dst, b, h) do { _Pragma("unroll") for (int n = 0; n < 2; ++n) _Pragma("unroll") for (int k = 0; k < 2; ++k) dst[n][k] = *(const PG8_LAS bf16x8*)(lds + PG8_SB(b, h) + boff + n * 2048 + k * 1024); } while (0)
; #define PG8_MMA(ai, bj, At, Bt) do { __builtin_amdgcn_s_setprio(1); _Pragma("unroll") for (int m = 0; m < 4; ++m) _Pragma("unroll") for (int n = 0; n < 2; ++n) _Pragma("unroll") for (int k = 0; k < 2; ++k) \
;         acc[ai][bj][m][n] = pg8_mma<F16>(Bt[n][k], At[m][k], acc[ai][bj][m][n]); __builtin_amdgcn_s_setprio(0); } while (0)
; #define PG8_WAIT_V(n) asm volatile("s_waitcnt vmcnt(" #n ")" ::: "memory")
; #define PG8_WAIT_L(n) asm volatile("s_waitcnt lgkmcnt(" #n ")" ::: "memory")
; #define PG8_BAR __builtin_amdgcn_s_barrier()
; #define PG8_SCHED __builtin_amdgcn_sched_barrier(0)
; template <class Epi, class Sched, bool ALIGN_EPI = false, bool SP2 = false, bool F16 = false>
; __device__ __forceinline__ void gemm_phase(PG8_LAS unsigned char* lds, const Gemm g, const Sched& S, const Epi& E) {
;     ...
;             PG8_LDB(B0, 0, 0); PG8_LDB(B1, 0, 1); PG8_SCHED; PG8_LDA(At, 0, 0); PG8_STAGE(PG8_SA(1, 1), a1 + hstep, voffA);
;             PG8_WAIT_V(8); PG8_WAIT_L(0); PG8_BAR; PG8_MMA(0, 0, At, B0); PG8_MMA(0, 1, At, B1); PG8_BAR; PG8_SCHED;
;             PG8_LDA(At, 0, 1); PG8_STAGE(PG8_SB(0, 0), b2, voffB); PG8_STAGE(PG8_SB(0, 1), b2 + hstep, voffB); PG8_STAGE(PG8_SA(0, 0), a2, voffA);
;             PG8_WAIT_V(8); PG8_WAIT_L(0); PG8_BAR; PG8_MMA(1, 0, At, B0); PG8_MMA(1, 1, At, B1); PG8_BAR; PG8_SCHED;
;             PG8_LDB(B0, 1, 0); PG8_LDB(B1, 1, 1); PG8_SCHED; PG8_LDA(At, 1, 0); PG8_STAGE(PG8_SA(0, 1), a2 + hstep, voffA);
;             PG8_WAIT_V(8); PG8_WAIT_L(0); PG8_BAR; PG8_MMA(0, 0, At, B0); PG8_MMA(0, 1, At, B1); PG8_BAR; PG8_SCHED;
.Lur_ip_d1:
	s_waitcnt lgkmcnt(0)
	s_barrier
	s_setprio 1
	s_waitcnt lgkmcnt(0)
	v_mfma_f32_16x16x32_bf16 v[62:65], v[146:149], v[178:181], v[62:65]
	v_mfma_f32_16x16x32_bf16 v[58:61], v[154:157], v[178:181], v[58:61]
	v_mfma_f32_16x16x32_bf16 v[54:57], v[146:149], v[186:189], v[54:57]
	v_mfma_f32_16x16x32_bf16 v[50:53], v[154:157], v[186:189], v[50:53]
	v_mfma_f32_16x16x32_bf16 v[38:41], v[146:149], v[194:197], v[38:41]
	v_mfma_f32_16x16x32_bf16 v[34:37], v[154:157], v[194:197], v[34:37]
	v_mfma_f32_16x16x32_bf16 v[22:25], v[146:149], v[202:205], v[22:25]
	v_mfma_f32_16x16x32_bf16 v[18:21], v[154:157], v[202:205], v[18:21]
	v_mfma_f32_16x16x32_bf16 v[62:65], v[150:153], v[182:185], v[62:65]
	v_mfma_f32_16x16x32_bf16 v[58:61], v[158:161], v[182:185], v[58:61]
	v_mfma_f32_16x16x32_bf16 v[54:57], v[150:153], v[190:193], v[54:57]
	v_mfma_f32_16x16x32_bf16 v[50:53], v[158:161], v[190:193], v[50:53]
	v_mfma_f32_16x16x32_bf16 v[38:41], v[150:153], v[198:201], v[38:41]
	v_mfma_f32_16x16x32_bf16 v[34:37], v[158:161], v[198:201], v[34:37]
	v_mfma_f32_16x16x32_bf16 v[22:25], v[150:153], v[206:209], v[22:25]
	v_mfma_f32_16x16x32_bf16 v[18:21], v[158:161], v[206:209], v[18:21]
	s_setprio 0
	s_setprio 1
	v_mfma_f32_16x16x32_bf16 v[46:49], v[162:165], v[178:181], v[46:49]
	v_mfma_f32_16x16x32_bf16 v[42:45], v[170:173], v[178:181], v[42:45]
	v_mfma_f32_16x16x32_bf16 v[30:33], v[162:165], v[186:189], v[30:33]
	v_mfma_f32_16x16x32_bf16 v[26:29], v[170:173], v[186:189], v[26:29]
	v_mfma_f32_16x16x32_bf16 v[14:17], v[162:165], v[194:197], v[14:17]
	v_mfma_f32_16x16x32_bf16 v[10:13], v[170:173], v[194:197], v[10:13]
	v_mfma_f32_16x16x32_bf16 v[6:9], v[162:165], v[202:205], v[6:9]
	v_mfma_f32_16x16x32_bf16 v[2:5], v[170:173], v[202:205], v[2:5]
	v_mfma_f32_16x16x32_bf16 v[46:49], v[166:169], v[182:185], v[46:49]
	v_mfma_f32_16x16x32_bf16 v[42:45], v[174:177], v[182:185], v[42:45]
	v_mfma_f32_16x16x32_bf16 v[30:33], v[166:169], v[190:193], v[30:33]
	v_mfma_f32_16x16x32_bf16 v[26:29], v[174:177], v[190:193], v[26:29]
	v_mfma_f32_16x16x32_bf16 v[14:17], v[166:169], v[198:201], v[14:17]
	v_mfma_f32_16x16x32_bf16 v[10:13], v[174:177], v[198:201], v[10:13]
	v_mfma_f32_16x16x32_bf16 v[6:9], v[166:169], v[206:209], v[6:9]
	v_mfma_f32_16x16x32_bf16 v[2:5], v[174:177], v[206:209], v[2:5]
	s_setprio 0
	s_barrier
	s_add_i32 s72, 0, 0x18000
	s_add_i32 s73, 0, 0x1c000
	v_add_u32_e32 v158, s72, v143
	v_add_u32_e32 v174, s73, v143
	ds_read_b128 v[146:149], v158
	ds_read_b128 v[150:153], v158 offset:1024
	ds_read_b128 v[154:157], v158 offset:2048
	ds_read_b128 v[158:161], v158 offset:3072
	ds_read_b128 v[162:165], v174
	ds_read_b128 v[166:169], v174 offset:1024
	ds_read_b128 v[170:173], v174 offset:2048
	ds_read_b128 v[174:177], v174 offset:3072
	s_add_u32 s46, s46, 0x80000
	s_addc_u32 s47, s47, 0
	s_mov_b32 m0, s61
	v_lshl_add_u64 v[224:225], s[46:47], 0, v[134:135]
	ds_read_b128 v[178:181], v145 offset:32768
	ds_read_b128 v[182:185], v145 offset:33792
	ds_read_b128 v[186:189], v145 offset:34816
	ds_read_b128 v[190:193], v145 offset:35840
	ds_read_b128 v[194:197], v145 offset:36864
	ds_read_b128 v[198:201], v145 offset:37888
	ds_read_b128 v[202:205], v145 offset:38912
	ds_read_b128 v[206:209], v145 offset:39936
	global_load_lds_dwordx4 v[224:225], off
	v_lshl_add_u64 v[224:225], s[46:47], 0, v[132:133]
	s_mov_b32 m0, s62
	s_nop 0
	global_load_lds_dwordx4 v[224:225], off
	s_waitcnt vmcnt(8)
	s_waitcnt lgkmcnt(0)
	s_barrier
	s_setprio 1
	s_waitcnt lgkmcnt(0)
	v_mfma_f32_16x16x32_bf16 v[126:129], v[146:149], v[178:181], v[126:129]
	v_mfma_f32_16x16x32_bf16 v[122:125], v[154:157], v[178:181], v[122:125]
	v_mfma_f32_16x16x32_bf16 v[118:121], v[146:149], v[186:189], v[118:121]
	v_mfma_f32_16x16x32_bf16 v[114:117], v[154:157], v[186:189], v[114:117]
	v_mfma_f32_16x16x32_bf16 v[102:105], v[146:149], v[194:197], v[102:105]
	v_mfma_f32_16x16x32_bf16 v[98:101], v[154:157], v[194:197], v[98:101]
	v_mfma_f32_16x16x32_bf16 v[86:89], v[146:149], v[202:205], v[86:89]
	v_mfma_f32_16x16x32_bf16 v[82:85], v[154:157], v[202:205], v[82:85]
	v_mfma_f32_16x16x32_bf16 v[126:129], v[150:153], v[182:185], v[126:129]
	v_mfma_f32_16x16x32_bf16 v[122:125], v[158:161], v[182:185], v[122:125]
	v_mfma_f32_16x16x32_bf16 v[118:121], v[150:153], v[190:193], v[118:121]
	v_mfma_f32_16x16x32_bf16 v[114:117], v[158:161], v[190:193], v[114:117]
	v_mfma_f32_16x16x32_bf16 v[102:105], v[150:153], v[198:201], v[102:105]
	v_mfma_f32_16x16x32_bf16 v[98:101], v[158:161], v[198:201], v[98:101]
	v_mfma_f32_16x16x32_bf16 v[86:89], v[150:153], v[206:209], v[86:89]
	v_mfma_f32_16x16x32_bf16 v[82:85], v[158:161], v[206:209], v[82:85]
	s_setprio 0
	s_setprio 1
	v_mfma_f32_16x16x32_bf16 v[110:113], v[162:165], v[178:181], v[110:113]
	v_mfma_f32_16x16x32_bf16 v[106:109], v[170:173], v[178:181], v[106:109]
	v_mfma_f32_16x16x32_bf16 v[94:97], v[162:165], v[186:189], v[94:97]
	v_mfma_f32_16x16x32_bf16 v[90:93], v[170:173], v[186:189], v[90:93]
	v_mfma_f32_16x16x32_bf16 v[78:81], v[162:165], v[194:197], v[78:81]
	v_mfma_f32_16x16x32_bf16 v[74:77], v[170:173], v[194:197], v[74:77]
	v_mfma_f32_16x16x32_bf16 v[70:73], v[162:165], v[202:205], v[70:73]
	v_mfma_f32_16x16x32_bf16 v[66:69], v[170:173], v[202:205], v[66:69]
	v_mfma_f32_16x16x32_bf16 v[110:113], v[166:169], v[182:185], v[110:113]
	v_mfma_f32_16x16x32_bf16 v[106:109], v[174:177], v[182:185], v[106:109]
	v_mfma_f32_16x16x32_bf16 v[94:97], v[166:169], v[190:193], v[94:97]
	v_mfma_f32_16x16x32_bf16 v[90:93], v[174:177], v[190:193], v[90:93]
	v_mfma_f32_16x16x32_bf16 v[78:81], v[166:169], v[198:201], v[78:81]
	v_mfma_f32_16x16x32_bf16 v[74:77], v[174:177], v[198:201], v[74:77]
	v_mfma_f32_16x16x32_bf16 v[70:73], v[166:169], v[206:209], v[70:73]
	v_mfma_f32_16x16x32_bf16 v[66:69], v[174:177], v[206:209], v[66:69]
	s_setprio 0
	s_barrier
; #define PG8_STAGE(bufoff, gbase, voff) do { _Pragma("unroll") for (int _i = 0; _i < 2; ++_i) \
;         __builtin_amdgcn_global_load_lds((const unsigned*)((const char*)(gbase) + (voff)[_i]), (PG8_LAS unsigned*)(lds + (bufoff) + ldsw + _i * 8192), 16, 0, 0); } while (0)
; #define PG8_LDA(dst, b, h) do { _Pragma("unroll") for (int m = 0; m < 4; ++m) _Pragma("unroll") for (int k = 0; k < 2; ++k) dst[m][k] = *(const PG8_LAS bf16x8*)(lds + PG8_SA(b, h) + aoff + m * 2048 + k * 1024); } while (0)
; #define PG8_LDB(dst, b, h) do { _Pragma("unroll") for (int n = 0; n < 2; ++n) _Pragma("unroll") for (int k = 0; k < 2; ++k) dst[n][k] = *(const PG8_LAS bf16x8*)(lds + PG8_SB(b, h) + boff + n * 2048 + k * 1024); } while (0)
; #define PG8_MMA(ai, bj, At, Bt) do { __builtin_amdgcn_s_setprio(1); _Pragma("unroll") for (int m = 0; m < 4; ++m) _Pragma("unroll") for (int n = 0; n < 2; ++n) _Pragma("unroll") for (int k = 0; k < 2; ++k) \
;         acc[ai][bj][m][n] = pg8_mma<F16>(Bt[n][k], At[m][k], acc[ai][bj][m][n]); __builtin_amdgcn_s_setprio(0); } while (0)
; #define PG8_WAIT_V(n) asm volatile("s_waitcnt vmcnt(" #n ")" ::: "memory")
; #define PG8_WAIT_L(n) asm volatile("s_waitcnt lgkmcnt(" #n ")" ::: "memory")
; #define PG8_BAR __builtin_amdgcn_s_barrier()
; #define PG8_SCHED __builtin_amdgcn_sched_barrier(0)
; template <class Epi, class Sched, bool ALIGN_EPI = false, bool SP2 = false, bool F16 = false>
; __device__ __forceinline__ void gemm_phase(PG8_LAS unsigned char* lds, const Gemm g, const Sched& S, const Epi& E) {
;     ...
;             PG8_LDB(B0, 1, 0); PG8_LDB(B1, 1, 1); PG8_SCHED; PG8_LDA(At, 1, 0); PG8_STAGE(PG8_SA(0, 1), a2 + hstep, voffA);
;             PG8_WAIT_V(8); PG8_WAIT_L(0); PG8_BAR; PG8_MMA(0, 0, At, B0); PG8_MMA(0, 1, At, B1); PG8_BAR; PG8_SCHED;
;             PG8_LDA(At, 1, 1); PG8_STAGE(PG8_SB(1, 0), b3, voffB); PG8_STAGE(PG8_SB(1, 1), b3 + hstep, voffB); PG8_STAGE(PG8_SA(1, 0), a3, voffA);
;             PG8_WAIT_V(8); PG8_WAIT_L(0); PG8_BAR; PG8_MMA(1, 0, At, B0); PG8_MMA(1, 1, At, B1); PG8_BAR; PG8_SCHED;
	s_add_i32 s46, s72, s52
	v_lshl_add_u64 v[210:211], v[210:211], 0, s[24:25]
	s_mov_b32 m0, s46
	ds_read_b128 v[178:181], v145 offset:49152
	ds_read_b128 v[182:185], v145 offset:50176
	ds_read_b128 v[186:189], v145 offset:51200
	ds_read_b128 v[190:193], v145 offset:52224
	ds_read_b128 v[194:197], v145 offset:53248
	ds_read_b128 v[198:201], v145 offset:54272
	ds_read_b128 v[202:205], v145 offset:55296
	ds_read_b128 v[206:209], v145 offset:56320
	global_load_lds_dwordx4 v[210:211], off
	s_add_i32 m0, s46, 0x2000
	s_add_u32 s44, s44, 0x80080
	v_lshl_add_u64 v[210:211], v[214:215], 0, s[24:25]
	s_addc_u32 s45, s45, 0
	s_add_i32 s46, s73, s52
	global_load_lds_dwordx4 v[210:211], off
	v_lshl_add_u64 v[210:211], s[44:45], 0, v[0:1]
	s_mov_b32 m0, s46
	s_nop 0
	global_load_lds_dwordx4 v[210:211], off
	v_lshl_add_u64 v[210:211], s[44:45], 0, v[130:131]
	s_add_i32 m0, s46, 0x2000
	s_nop 0
	global_load_lds_dwordx4 v[210:211], off
	v_lshl_add_u64 v[210:211], v[220:221], 0, s[24:25]
	s_mov_b32 m0, s63
	s_nop 0
	global_load_lds_dwordx4 v[210:211], off
	v_lshl_add_u64 v[210:211], v[222:223], 0, s[24:25]
	s_mov_b32 m0, s64
	s_nop 0
	global_load_lds_dwordx4 v[210:211], off
	s_waitcnt vmcnt(8)
	s_waitcnt lgkmcnt(0)
	s_barrier
	s_setprio 1
	s_waitcnt lgkmcnt(0)
	v_mfma_f32_16x16x32_bf16 v[62:65], v[146:149], v[178:181], v[62:65]
	v_mfma_f32_16x16x32_bf16 v[58:61], v[154:157], v[178:181], v[58:61]
	v_mfma_f32_16x16x32_bf16 v[54:57], v[146:149], v[186:189], v[54:57]
	v_mfma_f32_16x16x32_bf16 v[50:53], v[154:157], v[186:189], v[50:53]
	v_mfma_f32_16x16x32_bf16 v[38:41], v[146:149], v[194:197], v[38:41]
	v_mfma_f32_16x16x32_bf16 v[34:37], v[154:157], v[194:197], v[34:37]
	v_mfma_f32_16x16x32_bf16 v[22:25], v[146:149], v[202:205], v[22:25]
	v_mfma_f32_16x16x32_bf16 v[18:21], v[154:157], v[202:205], v[18:21]
	v_mfma_f32_16x16x32_bf16 v[62:65], v[150:153], v[182:185], v[62:65]
	v_mfma_f32_16x16x32_bf16 v[58:61], v[158:161], v[182:185], v[58:61]
	v_mfma_f32_16x16x32_bf16 v[54:57], v[150:153], v[190:193], v[54:57]
	v_mfma_f32_16x16x32_bf16 v[50:53], v[158:161], v[190:193], v[50:53]
	v_mfma_f32_16x16x32_bf16 v[38:41], v[150:153], v[198:201], v[38:41]
	v_mfma_f32_16x16x32_bf16 v[34:37], v[158:161], v[198:201], v[34:37]
	v_mfma_f32_16x16x32_bf16 v[22:25], v[150:153], v[206:209], v[22:25]
	v_mfma_f32_16x16x32_bf16 v[18:21], v[158:161], v[206:209], v[18:21]
	s_setprio 0
	s_setprio 1
	v_mfma_f32_16x16x32_bf16 v[46:49], v[162:165], v[178:181], v[46:49]
	v_mfma_f32_16x16x32_bf16 v[42:45], v[170:173], v[178:181], v[42:45]
	v_mfma_f32_16x16x32_bf16 v[30:33], v[162:165], v[186:189], v[30:33]
	v_mfma_f32_16x16x32_bf16 v[26:29], v[170:173], v[186:189], v[26:29]
	v_mfma_f32_16x16x32_bf16 v[14:17], v[162:165], v[194:197], v[14:17]
	v_mfma_f32_16x16x32_bf16 v[10:13], v[170:173], v[194:197], v[10:13]
	v_mfma_f32_16x16x32_bf16 v[6:9], v[162:165], v[202:205], v[6:9]
	v_mfma_f32_16x16x32_bf16 v[2:5], v[170:173], v[202:205], v[2:5]
	s_add_i32 s71, s71, 2
	s_add_u32 s42, s42, 0x100
	s_addc_u32 s43, s43, 0
	s_add_u32 s69, s69, 0x100
	s_addc_u32 s70, s70, 0
	s_add_u32 s44, s42, 0xfff80080
	s_addc_u32 s45, s43, -1
	s_add_i32 s72, 0, 0x10000
	s_cmp_eq_u32 s71, 28
	s_cselect_b32 s47, s21, s45
	s_cselect_b32 s46, s67, s44
	s_cselect_b32 s45, s19, s70
	s_cselect_b32 s44, s68, s69
	s_add_i32 s76, 0, 0x14000
	s_cmp_gt_u32 s71, 29
	v_mfma_f32_16x16x32_bf16 v[46:49], v[166:169], v[182:185], v[46:49]
	v_mfma_f32_16x16x32_bf16 v[42:45], v[174:177], v[182:185], v[42:45]
	v_mfma_f32_16x16x32_bf16 v[30:33], v[166:169], v[190:193], v[30:33]
	v_mfma_f32_16x16x32_bf16 v[26:29], v[174:177], v[190:193], v[26:29]
	v_mfma_f32_16x16x32_bf16 v[14:17], v[166:169], v[198:201], v[14:17]
	v_mfma_f32_16x16x32_bf16 v[10:13], v[174:177], v[198:201], v[10:13]
	v_mfma_f32_16x16x32_bf16 v[6:9], v[166:169], v[206:209], v[6:9]
	v_mfma_f32_16x16x32_bf16 v[2:5], v[174:177], v[206:209], v[2:5]
	s_setprio 0
	s_barrier
	s_cbranch_scc0 .LBB0_507
	s_and_b64 vcc, exec, s[16:17]
	s_cbranch_vccz .LBB0_510
	s_barrier

; #define PG8_STAGE(bufoff, gbase, voff) do { _Pragma("unroll") for (int _i = 0; _i < 2; ++_i) \
;         __builtin_amdgcn_global_load_lds((const unsigned*)((const char*)(gbase) + (voff)[_i]), (PG8_LAS unsigned*)(lds + (bufoff) + ldsw + _i * 8192), 16, 0, 0); } while (0)
; #define PG8_LDA(dst, b, h) do { _Pragma("unroll") for (int m = 0; m < 4; ++m) _Pragma("unroll") for (int k = 0; k < 2; ++k) dst[m][k] = *(const PG8_LAS bf16x8*)(lds + PG8_SA(b, h) + aoff + m * 2048 + k * 1024); } while (0)
; #define PG8_LDB(dst, b, h) do { _Pragma("unroll") for (int n = 0; n < 2; ++n) _Pragma("unroll") for (int k = 0; k < 2; ++k) dst[n][k] = *(const PG8_LAS bf16x8*)(lds + PG8_SB(b, h) + boff + n * 2048 + k * 1024); } while (0)
; #define PG8_SCHED __builtin_amdgcn_sched_barrier(0)
; template <class Epi, class Sched, bool ALIGN_EPI = false, bool SP2 = false, bool F16 = false>
; __device__ __forceinline__ void gemm_phase(PG8_LAS unsigned char* lds, const Gemm g, const Sched& S, const Epi& E) {
;     ...
;     f32x4 acc[2][2][4][2];
; #pragma unroll
;     for (int a = 0; a < 2; ++a)
; #pragma unroll
;         for (int b = 0; b < 2; ++b)
; #pragma unroll
;             for (int m = 0; m < 4; ++m)
; #pragma unroll
;                 for (int n = 0; n < 2; ++n) acc[a][b][m][n] = (f32x4){0.f, 0.f, 0.f, 0.f};
;     ...
;     for (;;) {
;         const bool has_next = S.next(ui + 1, nxt);
;         const char* nA = has_next ? (const char*)g.A + (size_t)nxt.pm * tstep : cA; const char* nB = has_next ? (const char*)g.Bt + (size_t)nxt.pn * tstep : cB;
;         for (int t = 0; t < nt; t += 2) {
;             const bool last = (t == nt - 2);
;             const char* a1 = cA + (size_t)(t + 1) * kstep;
;             const char* a2 = last ? nA : cA + (size_t)(t + 2) * kstep; const char* b2 = last ? nB : cB + (size_t)(t + 2) * kstep;
;             const char* a3 = a2 + kstep; const char* b3 = b2 + kstep;
;             if (last && has_next) S.a_ready(nxt);
;             if constexpr (SP2) {
;             PG8_LDB(B0, 0, 0); PG8_LDB(B1, 0, 1); PG8_SCHED; PG8_LDA(At, 0, 0); PG8_STAGE(PG8_SA(1, 1), a1 + hstep, voffA);
.LBB0_1635:
	s_ashr_i32 s53, s52, 31
	s_lshl_b64 s[8:9], s[52:53], 19
	s_add_u32 s54, s42, s8
	s_addc_u32 s55, s43, s9
	s_and_b64 s[8:9], s[38:39], exec
	s_cselect_b32 s53, s55, s1
	s_cselect_b32 s59, s54, s0
	s_ashr_i32 s51, s50, 31
	s_lshl_b64 s[8:9], s[50:51], 19
	s_add_u32 s56, s11, s8
	s_addc_u32 s57, s12, s9
	s_and_b64 s[8:9], s[38:39], exec
	s_cselect_b32 s51, s57, s7
	s_cselect_b32 s60, s56, s6
	s_add_u32 s0, s0, 0x40080
	s_addc_u32 s1, s1, 0
	s_add_u32 s61, s6, 0x100
	v_mov_b32_e32 v2, 0
	s_addc_u32 s62, s7, 0
	s_mov_b32 s63, -2
	v_mov_b32_e32 v3, v2
	v_mov_b32_e32 v4, v2
	v_mov_b32_e32 v5, v2
	v_mov_b32_e32 v6, v2
	v_mov_b32_e32 v7, v2
	v_mov_b32_e32 v8, v2
	v_mov_b32_e32 v9, v2
	v_mov_b32_e32 v18, v2
	v_mov_b32_e32 v19, v2
	v_mov_b32_e32 v20, v2
	v_mov_b32_e32 v21, v2
	v_mov_b32_e32 v22, v2
	v_mov_b32_e32 v23, v2
	v_mov_b32_e32 v24, v2
	v_mov_b32_e32 v25, v2
	v_mov_b32_e32 v34, v2
	v_mov_b32_e32 v35, v2
	v_mov_b32_e32 v36, v2
	v_mov_b32_e32 v37, v2
	v_mov_b32_e32 v38, v2
	v_mov_b32_e32 v39, v2
	v_mov_b32_e32 v40, v2
	v_mov_b32_e32 v41, v2
	v_mov_b32_e32 v50, v2
	v_mov_b32_e32 v51, v2
	v_mov_b32_e32 v52, v2
	v_mov_b32_e32 v53, v2
	v_mov_b32_e32 v54, v2
	v_mov_b32_e32 v55, v2
	v_mov_b32_e32 v56, v2
	v_mov_b32_e32 v57, v2
	v_mov_b32_e32 v10, v2
	v_mov_b32_e32 v11, v2
	v_mov_b32_e32 v12, v2
	v_mov_b32_e32 v13, v2
	v_mov_b32_e32 v14, v2
	v_mov_b32_e32 v15, v2
	v_mov_b32_e32 v16, v2
	v_mov_b32_e32 v17, v2
	v_mov_b32_e32 v26, v2
	v_mov_b32_e32 v27, v2
	v_mov_b32_e32 v28, v2
	v_mov_b32_e32 v29, v2
	v_mov_b32_e32 v30, v2
	v_mov_b32_e32 v31, v2
	v_mov_b32_e32 v32, v2
	v_mov_b32_e32 v33, v2
	v_mov_b32_e32 v42, v2
	v_mov_b32_e32 v43, v2
	v_mov_b32_e32 v44, v2
	v_mov_b32_e32 v45, v2
	v_mov_b32_e32 v46, v2
	v_mov_b32_e32 v47, v2
	v_mov_b32_e32 v48, v2
	v_mov_b32_e32 v49, v2
	v_mov_b32_e32 v58, v2
	v_mov_b32_e32 v59, v2
	v_mov_b32_e32 v60, v2
	v_mov_b32_e32 v61, v2
	v_mov_b32_e32 v62, v2
	v_mov_b32_e32 v63, v2
	v_mov_b32_e32 v64, v2
	v_mov_b32_e32 v65, v2
	v_mov_b32_e32 v66, v2
	v_mov_b32_e32 v67, v2
	v_mov_b32_e32 v68, v2
	v_mov_b32_e32 v69, v2
	v_mov_b32_e32 v70, v2
	v_mov_b32_e32 v71, v2
	v_mov_b32_e32 v72, v2
	v_mov_b32_e32 v73, v2
	v_mov_b32_e32 v82, v2
	v_mov_b32_e32 v83, v2
	v_mov_b32_e32 v84, v2
	v_mov_b32_e32 v85, v2
	v_mov_b32_e32 v86, v2
	v_mov_b32_e32 v87, v2
	v_mov_b32_e32 v88, v2
	v_mov_b32_e32 v89, v2
	v_mov_b32_e32 v98, v2
	v_mov_b32_e32 v99, v2
	v_mov_b32_e32 v100, v2
	v_mov_b32_e32 v101, v2
	v_mov_b32_e32 v102, v2
	v_mov_b32_e32 v103, v2
	v_mov_b32_e32 v104, v2
	v_mov_b32_e32 v105, v2
	v_mov_b32_e32 v114, v2
	v_mov_b32_e32 v115, v2
	v_mov_b32_e32 v116, v2
	v_mov_b32_e32 v117, v2
	v_mov_b32_e32 v118, v2
	v_mov_b32_e32 v119, v2
	v_mov_b32_e32 v120, v2
	v_mov_b32_e32 v121, v2
	v_mov_b32_e32 v74, v2
	v_mov_b32_e32 v75, v2
	v_mov_b32_e32 v76, v2
	v_mov_b32_e32 v77, v2
	v_mov_b32_e32 v78, v2
	v_mov_b32_e32 v79, v2
	v_mov_b32_e32 v80, v2
	v_mov_b32_e32 v81, v2
	v_mov_b32_e32 v90, v2
	v_mov_b32_e32 v91, v2
	v_mov_b32_e32 v92, v2
	v_mov_b32_e32 v93, v2
	v_mov_b32_e32 v94, v2
	v_mov_b32_e32 v95, v2
	v_mov_b32_e32 v96, v2
	v_mov_b32_e32 v97, v2
	v_mov_b32_e32 v106, v2
	v_mov_b32_e32 v107, v2
	v_mov_b32_e32 v108, v2
	v_mov_b32_e32 v109, v2
	v_mov_b32_e32 v110, v2
	v_mov_b32_e32 v111, v2
	v_mov_b32_e32 v112, v2
	v_mov_b32_e32 v113, v2
	v_mov_b32_e32 v122, v2
	v_mov_b32_e32 v123, v2
	v_mov_b32_e32 v124, v2
	v_mov_b32_e32 v125, v2
	v_mov_b32_e32 v126, v2
	v_mov_b32_e32 v127, v2
	v_mov_b32_e32 v128, v2
	v_mov_b32_e32 v129, v2
	s_add_u32 s6, s0, 0xfffc0080
	s_addc_u32 s7, s1, -1
	s_add_i32 s64, 0, 0x10000
	s_cmp_eq_u32 s63, 12
	s_cselect_b32 s9, s53, s7
	s_cselect_b32 s8, s59, s6
	s_cselect_b32 s7, s51, s62
	s_cselect_b32 s6, s60, s61
	s_add_i32 s66, 0, 0x14000
.LBB0_1636:
	v_add_u32_e32 v156, s64, v145
	v_add_u32_e32 v172, s66, v145
	ds_read_b128 v[140:143], v156
	ds_read_b128 v[148:151], v156 offset:1024
	ds_read_b128 v[152:155], v156 offset:2048
	ds_read_b128 v[156:159], v156 offset:3072
	ds_read_b128 v[160:163], v172
	ds_read_b128 v[164:167], v172 offset:1024
	ds_read_b128 v[168:171], v172 offset:2048
	ds_read_b128 v[172:175], v172 offset:3072
	v_lshl_add_u64 v[208:209], s[0:1], 0, v[136:137]
	s_add_i32 m0, s15, 0xc000
	ds_read_b128 v[176:179], v147
	ds_read_b128 v[180:183], v147 offset:1024
	ds_read_b128 v[184:187], v147 offset:2048
	ds_read_b128 v[188:191], v147 offset:3072
	ds_read_b128 v[192:195], v147 offset:4096
	ds_read_b128 v[196:199], v147 offset:5120
	ds_read_b128 v[200:203], v147 offset:6144
	ds_read_b128 v[204:207], v147 offset:7168
	global_load_lds_dwordx4 v[208:209], off
	v_lshl_add_u64 v[208:209], s[0:1], 0, v[138:139]
	s_add_i32 m0, s15, 0xe000
	s_nop 0
	global_load_lds_dwordx4 v[208:209], off
	s_waitcnt vmcnt(8)
	s_waitcnt lgkmcnt(0)
	s_barrier
; #define PG8_STAGE(bufoff, gbase, voff) do { _Pragma("unroll") for (int _i = 0; _i < 2; ++_i) \
;         __builtin_amdgcn_global_load_lds((const unsigned*)((const char*)(gbase) + (voff)[_i]), (PG8_LAS unsigned*)(lds + (bufoff) + ldsw + _i * 8192), 16, 0, 0); } while (0)
; #define PG8_LDA(dst, b, h) do { _Pragma("unroll") for (int m = 0; m < 4; ++m) _Pragma("unroll") for (int k = 0; k < 2; ++k) dst[m][k] = *(const PG8_LAS bf16x8*)(lds + PG8_SA(b, h) + aoff + m * 2048 + k * 1024); } while (0)
; #define PG8_LDB(dst, b, h) do { _Pragma("unroll") for (int n = 0; n < 2; ++n) _Pragma("unroll") for (int k = 0; k < 2; ++k) dst[n][k] = *(const PG8_LAS bf16x8*)(lds + PG8_SB(b, h) + boff + n * 2048 + k * 1024); } while (0)
; #define PG8_MMA(ai, bj, At, Bt) do { __builtin_amdgcn_s_setprio(1); _Pragma("unroll") for (int m = 0; m < 4; ++m) _Pragma("unroll") for (int n = 0; n < 2; ++n) _Pragma("unroll") for (int k = 0; k < 2; ++k) \
;         acc[ai][bj][m][n] = pg8_mma<F16>(Bt[n][k], At[m][k], acc[ai][bj][m][n]); __builtin_amdgcn_s_setprio(0); } while (0)
; #define PG8_WAIT_V(n) asm volatile("s_waitcnt vmcnt(" #n ")" ::: "memory")
; #define PG8_WAIT_L(n) asm volatile("s_waitcnt lgkmcnt(" #n ")" ::: "memory")
; #define PG8_BAR __builtin_amdgcn_s_barrier()
; #define PG8_SCHED __builtin_amdgcn_sched_barrier(0)
; template <class Epi, class Sched, bool ALIGN_EPI = false, bool SP2 = false, bool F16 = false>
; __device__ __forceinline__ void gemm_phase(PG8_LAS unsigned char* lds, const Gemm g, const Sched& S, const Epi& E) {
;     ...
;             PG8_LDB(B0, 0, 0); PG8_LDB(B1, 0, 1); PG8_SCHED; PG8_LDA(At, 0, 0); PG8_STAGE(PG8_SA(1, 1), a1 + hstep, voffA);
;             PG8_WAIT_V(8); PG8_WAIT_L(0); PG8_BAR; PG8_MMA(0, 0, At, B0); PG8_MMA(0, 1, At, B1); PG8_BAR; PG8_SCHED;
;             PG8_LDA(At, 0, 1); PG8_STAGE(PG8_SB(0, 0), b2, voffB); PG8_STAGE(PG8_SB(0, 1), b2 + hstep, voffB); PG8_STAGE(PG8_SA(0, 0), a2, voffA);
;             PG8_WAIT_V(8); PG8_WAIT_L(0); PG8_BAR; PG8_MMA(1, 0, At, B0); PG8_MMA(1, 1, At, B1); PG8_BAR; PG8_SCHED;
;             PG8_LDB(B0, 1, 0); PG8_LDB(B1, 1, 1); PG8_SCHED; PG8_LDA(At, 1, 0); PG8_STAGE(PG8_SA(0, 1), a2 + hstep, voffA);
;             PG8_WAIT_V(8); PG8_WAIT_L(0); PG8_BAR; PG8_MMA(0, 0, At, B0); PG8_MMA(0, 1, At, B1); PG8_BAR; PG8_SCHED;
	s_setprio 1
	s_waitcnt lgkmcnt(0)
	v_mfma_f32_16x16x32_bf16 v[126:129], v[140:143], v[176:179], v[126:129]
	v_mfma_f32_16x16x32_bf16 v[122:125], v[152:155], v[176:179], v[122:125]
	v_mfma_f32_16x16x32_bf16 v[110:113], v[140:143], v[184:187], v[110:113]
	v_mfma_f32_16x16x32_bf16 v[106:109], v[152:155], v[184:187], v[106:109]
	v_mfma_f32_16x16x32_bf16 v[94:97], v[140:143], v[192:195], v[94:97]
	v_mfma_f32_16x16x32_bf16 v[90:93], v[152:155], v[192:195], v[90:93]
	v_mfma_f32_16x16x32_bf16 v[78:81], v[140:143], v[200:203], v[78:81]
	v_mfma_f32_16x16x32_bf16 v[74:77], v[152:155], v[200:203], v[74:77]
	v_mfma_f32_16x16x32_bf16 v[126:129], v[148:151], v[180:183], v[126:129]
	v_mfma_f32_16x16x32_bf16 v[122:125], v[156:159], v[180:183], v[122:125]
	v_mfma_f32_16x16x32_bf16 v[110:113], v[148:151], v[188:191], v[110:113]
	v_mfma_f32_16x16x32_bf16 v[106:109], v[156:159], v[188:191], v[106:109]
	v_mfma_f32_16x16x32_bf16 v[94:97], v[148:151], v[196:199], v[94:97]
	v_mfma_f32_16x16x32_bf16 v[90:93], v[156:159], v[196:199], v[90:93]
	v_mfma_f32_16x16x32_bf16 v[78:81], v[148:151], v[204:207], v[78:81]
	v_mfma_f32_16x16x32_bf16 v[74:77], v[156:159], v[204:207], v[74:77]
	s_setprio 0
	s_setprio 1
	v_mfma_f32_16x16x32_bf16 v[118:121], v[160:163], v[176:179], v[118:121]
	v_mfma_f32_16x16x32_bf16 v[114:117], v[168:171], v[176:179], v[114:117]
	v_mfma_f32_16x16x32_bf16 v[102:105], v[160:163], v[184:187], v[102:105]
	v_mfma_f32_16x16x32_bf16 v[98:101], v[168:171], v[184:187], v[98:101]
	v_mfma_f32_16x16x32_bf16 v[86:89], v[160:163], v[192:195], v[86:89]
	v_mfma_f32_16x16x32_bf16 v[82:85], v[168:171], v[192:195], v[82:85]
	v_mfma_f32_16x16x32_bf16 v[70:73], v[160:163], v[200:203], v[70:73]
	v_mfma_f32_16x16x32_bf16 v[66:69], v[168:171], v[200:203], v[66:69]
	v_mfma_f32_16x16x32_bf16 v[118:121], v[164:167], v[180:183], v[118:121]
	v_mfma_f32_16x16x32_bf16 v[114:117], v[172:175], v[180:183], v[114:117]
	v_mfma_f32_16x16x32_bf16 v[102:105], v[164:167], v[188:191], v[102:105]
	v_mfma_f32_16x16x32_bf16 v[98:101], v[172:175], v[188:191], v[98:101]
	v_mfma_f32_16x16x32_bf16 v[86:89], v[164:167], v[196:199], v[86:89]
	v_mfma_f32_16x16x32_bf16 v[82:85], v[172:175], v[196:199], v[82:85]
	v_mfma_f32_16x16x32_bf16 v[70:73], v[164:167], v[204:207], v[70:73]
	v_mfma_f32_16x16x32_bf16 v[66:69], v[172:175], v[204:207], v[66:69]
	s_setprio 0
	s_barrier
	s_add_i32 s64, s64, s13
	v_lshl_add_u64 v[208:209], s[6:7], 0, v[0:1]
	s_mov_b32 m0, s64
	ds_read_b128 v[176:179], v147 offset:16384
	ds_read_b128 v[180:183], v147 offset:17408
	ds_read_b128 v[184:187], v147 offset:18432
	ds_read_b128 v[188:191], v147 offset:19456
	ds_read_b128 v[192:195], v147 offset:20480
	ds_read_b128 v[196:199], v147 offset:21504
	ds_read_b128 v[200:203], v147 offset:22528
	ds_read_b128 v[204:207], v147 offset:23552
	global_load_lds_dwordx4 v[208:209], off
	s_add_i32 m0, s64, 0x2000
	s_add_u32 s64, s6, 0x40000
	v_lshl_add_u64 v[210:211], s[6:7], 0, v[130:131]
	s_addc_u32 s65, s7, 0
	s_add_i32 s66, s66, s13
	global_load_lds_dwordx4 v[210:211], off
	v_lshl_add_u64 v[214:215], s[64:65], 0, v[0:1]
	s_mov_b32 m0, s66
	v_lshl_add_u64 v[220:221], s[8:9], 0, v[132:133]
	global_load_lds_dwordx4 v[214:215], off
	v_lshl_add_u64 v[214:215], s[64:65], 0, v[130:131]
	s_add_i32 m0, s66, 0x2000
	s_nop 0
	global_load_lds_dwordx4 v[214:215], off
	v_lshl_add_u64 v[214:215], s[8:9], 0, v[134:135]
	s_mov_b32 m0, s15
	s_nop 0
	global_load_lds_dwordx4 v[214:215], off
	s_mov_b32 m0, s18
	s_nop 0
	global_load_lds_dwordx4 v[220:221], off
	s_waitcnt vmcnt(8)
	s_waitcnt lgkmcnt(0)
	s_barrier
	s_setprio 1
	s_waitcnt lgkmcnt(0)
	v_mfma_f32_16x16x32_bf16 v[62:65], v[140:143], v[176:179], v[62:65]
	v_mfma_f32_16x16x32_bf16 v[58:61], v[152:155], v[176:179], v[58:61]
	v_mfma_f32_16x16x32_bf16 v[46:49], v[140:143], v[184:187], v[46:49]
	v_mfma_f32_16x16x32_bf16 v[42:45], v[152:155], v[184:187], v[42:45]
	v_mfma_f32_16x16x32_bf16 v[30:33], v[140:143], v[192:195], v[30:33]
	v_mfma_f32_16x16x32_bf16 v[26:29], v[152:155], v[192:195], v[26:29]
	v_mfma_f32_16x16x32_bf16 v[14:17], v[140:143], v[200:203], v[14:17]
	v_mfma_f32_16x16x32_bf16 v[10:13], v[152:155], v[200:203], v[10:13]
	v_mfma_f32_16x16x32_bf16 v[62:65], v[148:151], v[180:183], v[62:65]
	v_mfma_f32_16x16x32_bf16 v[58:61], v[156:159], v[180:183], v[58:61]
	v_mfma_f32_16x16x32_bf16 v[46:49], v[148:151], v[188:191], v[46:49]
	v_mfma_f32_16x16x32_bf16 v[42:45], v[156:159], v[188:191], v[42:45]
	v_mfma_f32_16x16x32_bf16 v[30:33], v[148:151], v[196:199], v[30:33]
	v_mfma_f32_16x16x32_bf16 v[26:29], v[156:159], v[196:199], v[26:29]
	v_mfma_f32_16x16x32_bf16 v[14:17], v[148:151], v[204:207], v[14:17]
	v_mfma_f32_16x16x32_bf16 v[10:13], v[156:159], v[204:207], v[10:13]
	s_setprio 0
	s_setprio 1
	v_mfma_f32_16x16x32_bf16 v[54:57], v[160:163], v[176:179], v[54:57]
	v_mfma_f32_16x16x32_bf16 v[50:53], v[168:171], v[176:179], v[50:53]
	v_mfma_f32_16x16x32_bf16 v[38:41], v[160:163], v[184:187], v[38:41]
	v_mfma_f32_16x16x32_bf16 v[34:37], v[168:171], v[184:187], v[34:37]
	v_mfma_f32_16x16x32_bf16 v[22:25], v[160:163], v[192:195], v[22:25]
	v_mfma_f32_16x16x32_bf16 v[18:21], v[168:171], v[192:195], v[18:21]
	v_mfma_f32_16x16x32_bf16 v[6:9], v[160:163], v[200:203], v[6:9]
	v_mfma_f32_16x16x32_bf16 v[2:5], v[168:171], v[200:203], v[2:5]
	v_mfma_f32_16x16x32_bf16 v[54:57], v[164:167], v[180:183], v[54:57]
	v_mfma_f32_16x16x32_bf16 v[50:53], v[172:175], v[180:183], v[50:53]
	v_mfma_f32_16x16x32_bf16 v[38:41], v[164:167], v[188:191], v[38:41]
	v_mfma_f32_16x16x32_bf16 v[34:37], v[172:175], v[188:191], v[34:37]
	v_mfma_f32_16x16x32_bf16 v[22:25], v[164:167], v[196:199], v[22:25]
	v_mfma_f32_16x16x32_bf16 v[18:21], v[172:175], v[196:199], v[18:21]
	v_mfma_f32_16x16x32_bf16 v[6:9], v[164:167], v[204:207], v[6:9]
	v_mfma_f32_16x16x32_bf16 v[2:5], v[172:175], v[204:207], v[2:5]
	s_setprio 0
	s_barrier
; #define PG8_STAGE(bufoff, gbase, voff) do { _Pragma("unroll") for (int _i = 0; _i < 2; ++_i) \
;         __builtin_amdgcn_global_load_lds((const unsigned*)((const char*)(gbase) + (voff)[_i]), (PG8_LAS unsigned*)(lds + (bufoff) + ldsw + _i * 8192), 16, 0, 0); } while (0)
; #define PG8_LDA(dst, b, h) do { _Pragma("unroll") for (int m = 0; m < 4; ++m) _Pragma("unroll") for (int k = 0; k < 2; ++k) dst[m][k] = *(const PG8_LAS bf16x8*)(lds + PG8_SA(b, h) + aoff + m * 2048 + k * 1024); } while (0)
; #define PG8_LDB(dst, b, h) do { _Pragma("unroll") for (int n = 0; n < 2; ++n) _Pragma("unroll") for (int k = 0; k < 2; ++k) dst[n][k] = *(const PG8_LAS bf16x8*)(lds + PG8_SB(b, h) + boff + n * 2048 + k * 1024); } while (0)
; #define PG8_MMA(ai, bj, At, Bt) do { __builtin_amdgcn_s_setprio(1); _Pragma("unroll") for (int m = 0; m < 4; ++m) _Pragma("unroll") for (int n = 0; n < 2; ++n) _Pragma("unroll") for (int k = 0; k < 2; ++k) \
;         acc[ai][bj][m][n] = pg8_mma<F16>(Bt[n][k], At[m][k], acc[ai][bj][m][n]); __builtin_amdgcn_s_setprio(0); } while (0)
; #define PG8_WAIT_V(n) asm volatile("s_waitcnt vmcnt(" #n ")" ::: "memory")
; #define PG8_WAIT_L(n) asm volatile("s_waitcnt lgkmcnt(" #n ")" ::: "memory")
; #define PG8_BAR __builtin_amdgcn_s_barrier()
; #define PG8_SCHED __builtin_amdgcn_sched_barrier(0)
; template <class Epi, class Sched, bool ALIGN_EPI = false, bool SP2 = false, bool F16 = false>
; __device__ __forceinline__ void gemm_phase(PG8_LAS unsigned char* lds, const Gemm g, const Sched& S, const Epi& E) {
;     ...
;             PG8_LDB(B0, 1, 0); PG8_LDB(B1, 1, 1); PG8_SCHED; PG8_LDA(At, 1, 0); PG8_STAGE(PG8_SA(0, 1), a2 + hstep, voffA);
;             PG8_WAIT_V(8); PG8_WAIT_L(0); PG8_BAR; PG8_MMA(0, 0, At, B0); PG8_MMA(0, 1, At, B1); PG8_BAR; PG8_SCHED;
	s_add_i32 s64, 0, 0x18000
	s_add_i32 s65, 0, 0x1c000
	v_add_u32_e32 v156, s64, v145
	v_add_u32_e32 v172, s65, v145
	ds_read_b128 v[140:143], v156
	ds_read_b128 v[148:151], v156 offset:1024
	ds_read_b128 v[152:155], v156 offset:2048
	ds_read_b128 v[156:159], v156 offset:3072
	ds_read_b128 v[160:163], v172
	ds_read_b128 v[164:167], v172 offset:1024
	ds_read_b128 v[168:171], v172 offset:2048
	ds_read_b128 v[172:175], v172 offset:3072
	s_add_u32 s8, s8, 0x40000
	s_addc_u32 s9, s9, 0
	s_mov_b32 m0, s19
	v_lshl_add_u64 v[222:223], s[8:9], 0, v[134:135]
	ds_read_b128 v[176:179], v147 offset:32768
	ds_read_b128 v[180:183], v147 offset:33792
	ds_read_b128 v[184:187], v147 offset:34816
	ds_read_b128 v[188:191], v147 offset:35840
	ds_read_b128 v[192:195], v147 offset:36864
	ds_read_b128 v[196:199], v147 offset:37888
	ds_read_b128 v[200:203], v147 offset:38912
	ds_read_b128 v[204:207], v147 offset:39936
	global_load_lds_dwordx4 v[222:223], off
	v_lshl_add_u64 v[222:223], s[8:9], 0, v[132:133]
	s_mov_b32 m0, s20
	s_nop 0
	global_load_lds_dwordx4 v[222:223], off
	s_waitcnt vmcnt(8)
	s_waitcnt lgkmcnt(0)
	s_barrier
	s_setprio 1
	s_waitcnt lgkmcnt(0)
	v_mfma_f32_16x16x32_bf16 v[126:129], v[140:143], v[176:179], v[126:129]
	v_mfma_f32_16x16x32_bf16 v[122:125], v[152:155], v[176:179], v[122:125]
	v_mfma_f32_16x16x32_bf16 v[110:113], v[140:143], v[184:187], v[110:113]
	v_mfma_f32_16x16x32_bf16 v[106:109], v[152:155], v[184:187], v[106:109]
	v_mfma_f32_16x16x32_bf16 v[94:97], v[140:143], v[192:195], v[94:97]
	v_mfma_f32_16x16x32_bf16 v[90:93], v[152:155], v[192:195], v[90:93]
	v_mfma_f32_16x16x32_bf16 v[78:81], v[140:143], v[200:203], v[78:81]
	v_mfma_f32_16x16x32_bf16 v[74:77], v[152:155], v[200:203], v[74:77]
	v_mfma_f32_16x16x32_bf16 v[126:129], v[148:151], v[180:183], v[126:129]
	v_mfma_f32_16x16x32_bf16 v[122:125], v[156:159], v[180:183], v[122:125]
	v_mfma_f32_16x16x32_bf16 v[110:113], v[148:151], v[188:191], v[110:113]
	v_mfma_f32_16x16x32_bf16 v[106:109], v[156:159], v[188:191], v[106:109]
	v_mfma_f32_16x16x32_bf16 v[94:97], v[148:151], v[196:199], v[94:97]
	v_mfma_f32_16x16x32_bf16 v[90:93], v[156:159], v[196:199], v[90:93]
	v_mfma_f32_16x16x32_bf16 v[78:81], v[148:151], v[204:207], v[78:81]
	v_mfma_f32_16x16x32_bf16 v[74:77], v[156:159], v[204:207], v[74:77]
	s_setprio 0
	s_setprio 1
	v_mfma_f32_16x16x32_bf16 v[118:121], v[160:163], v[176:179], v[118:121]
	v_mfma_f32_16x16x32_bf16 v[114:117], v[168:171], v[176:179], v[114:117]
	v_mfma_f32_16x16x32_bf16 v[102:105], v[160:163], v[184:187], v[102:105]
	v_mfma_f32_16x16x32_bf16 v[98:101], v[168:171], v[184:187], v[98:101]
	v_mfma_f32_16x16x32_bf16 v[86:89], v[160:163], v[192:195], v[86:89]
	v_mfma_f32_16x16x32_bf16 v[82:85], v[168:171], v[192:195], v[82:85]
	v_mfma_f32_16x16x32_bf16 v[70:73], v[160:163], v[200:203], v[70:73]
	v_mfma_f32_16x16x32_bf16 v[66:69], v[168:171], v[200:203], v[66:69]
	v_mfma_f32_16x16x32_bf16 v[118:121], v[164:167], v[180:183], v[118:121]
	v_mfma_f32_16x16x32_bf16 v[114:117], v[172:175], v[180:183], v[114:117]
	v_mfma_f32_16x16x32_bf16 v[102:105], v[164:167], v[188:191], v[102:105]
	v_mfma_f32_16x16x32_bf16 v[98:101], v[172:175], v[188:191], v[98:101]
	v_mfma_f32_16x16x32_bf16 v[86:89], v[164:167], v[196:199], v[86:89]
	v_mfma_f32_16x16x32_bf16 v[82:85], v[172:175], v[196:199], v[82:85]
	v_mfma_f32_16x16x32_bf16 v[70:73], v[164:167], v[204:207], v[70:73]
	v_mfma_f32_16x16x32_bf16 v[66:69], v[172:175], v[204:207], v[66:69]
	s_setprio 0
	s_barrier
; #define PG8_STAGE(bufoff, gbase, voff) do { _Pragma("unroll") for (int _i = 0; _i < 2; ++_i) \
;         __builtin_amdgcn_global_load_lds((const unsigned*)((const char*)(gbase) + (voff)[_i]), (PG8_LAS unsigned*)(lds + (bufoff) + ldsw + _i * 8192), 16, 0, 0); } while (0)
; #define PG8_LDA(dst, b, h) do { _Pragma("unroll") for (int m = 0; m < 4; ++m) _Pragma("unroll") for (int k = 0; k < 2; ++k) dst[m][k] = *(const PG8_LAS bf16x8*)(lds + PG8_SA(b, h) + aoff + m * 2048 + k * 1024); } while (0)
; #define PG8_MMA(ai, bj, At, Bt) do { __builtin_amdgcn_s_setprio(1); _Pragma("unroll") for (int m = 0; m < 4; ++m) _Pragma("unroll") for (int n = 0; n < 2; ++n) _Pragma("unroll") for (int k = 0; k < 2; ++k) \
;         acc[ai][bj][m][n] = pg8_mma<F16>(Bt[n][k], At[m][k], acc[ai][bj][m][n]); __builtin_amdgcn_s_setprio(0); } while (0)
; #define PG8_WAIT_V(n) asm volatile("s_waitcnt vmcnt(" #n ")" ::: "memory")
; #define PG8_WAIT_L(n) asm volatile("s_waitcnt lgkmcnt(" #n ")" ::: "memory")
; #define PG8_BAR __builtin_amdgcn_s_barrier()
; #define PG8_SCHED __builtin_amdgcn_sched_barrier(0)
; template <class Epi, class Sched, bool ALIGN_EPI = false, bool SP2 = false, bool F16 = false>
; __device__ __forceinline__ void gemm_phase(PG8_LAS unsigned char* lds, const Gemm g, const Sched& S, const Epi& E) {
;     ...
;             PG8_LDA(At, 1, 1); PG8_STAGE(PG8_SB(1, 0), b3, voffB); PG8_STAGE(PG8_SB(1, 1), b3 + hstep, voffB); PG8_STAGE(PG8_SA(1, 0), a3, voffA);
;             PG8_WAIT_V(8); PG8_WAIT_L(0); PG8_BAR; PG8_MMA(1, 0, At, B0); PG8_MMA(1, 1, At, B1); PG8_BAR; PG8_SCHED;
	s_add_i32 s8, s64, s13
	v_lshl_add_u64 v[208:209], v[208:209], 0, s[24:25]
	s_mov_b32 m0, s8
	ds_read_b128 v[176:179], v147 offset:49152
	ds_read_b128 v[180:183], v147 offset:50176
	ds_read_b128 v[184:187], v147 offset:51200
	ds_read_b128 v[188:191], v147 offset:52224
	ds_read_b128 v[192:195], v147 offset:53248
	ds_read_b128 v[196:199], v147 offset:54272
	ds_read_b128 v[200:203], v147 offset:55296
	ds_read_b128 v[204:207], v147 offset:56320
	global_load_lds_dwordx4 v[208:209], off
	s_add_i32 m0, s8, 0x2000
	s_add_u32 s6, s6, 0x40080
	v_lshl_add_u64 v[208:209], v[210:211], 0, s[24:25]
	s_addc_u32 s7, s7, 0
	s_add_i32 s8, s65, s13
	global_load_lds_dwordx4 v[208:209], off
	v_lshl_add_u64 v[208:209], s[6:7], 0, v[0:1]
	s_mov_b32 m0, s8
	s_nop 0
	global_load_lds_dwordx4 v[208:209], off
	v_lshl_add_u64 v[208:209], s[6:7], 0, v[130:131]
	s_add_i32 m0, s8, 0x2000
	s_nop 0
	global_load_lds_dwordx4 v[208:209], off
	v_lshl_add_u64 v[208:209], v[214:215], 0, s[24:25]
	s_mov_b32 m0, s21
	s_nop 0
	global_load_lds_dwordx4 v[208:209], off
	v_lshl_add_u64 v[208:209], v[220:221], 0, s[24:25]
	s_mov_b32 m0, s26
	s_nop 0
	global_load_lds_dwordx4 v[208:209], off
	s_waitcnt vmcnt(8)
	s_waitcnt lgkmcnt(0)
	s_barrier
	s_setprio 1
	s_waitcnt lgkmcnt(0)
	v_mfma_f32_16x16x32_bf16 v[62:65], v[140:143], v[176:179], v[62:65]
	v_mfma_f32_16x16x32_bf16 v[58:61], v[152:155], v[176:179], v[58:61]
	v_mfma_f32_16x16x32_bf16 v[46:49], v[140:143], v[184:187], v[46:49]
	v_mfma_f32_16x16x32_bf16 v[42:45], v[152:155], v[184:187], v[42:45]
	v_mfma_f32_16x16x32_bf16 v[30:33], v[140:143], v[192:195], v[30:33]
	v_mfma_f32_16x16x32_bf16 v[26:29], v[152:155], v[192:195], v[26:29]
	v_mfma_f32_16x16x32_bf16 v[14:17], v[140:143], v[200:203], v[14:17]
	v_mfma_f32_16x16x32_bf16 v[10:13], v[152:155], v[200:203], v[10:13]
	v_mfma_f32_16x16x32_bf16 v[62:65], v[148:151], v[180:183], v[62:65]
	v_mfma_f32_16x16x32_bf16 v[58:61], v[156:159], v[180:183], v[58:61]
	v_mfma_f32_16x16x32_bf16 v[46:49], v[148:151], v[188:191], v[46:49]
	v_mfma_f32_16x16x32_bf16 v[42:45], v[156:159], v[188:191], v[42:45]
	v_mfma_f32_16x16x32_bf16 v[30:33], v[148:151], v[196:199], v[30:33]
	v_mfma_f32_16x16x32_bf16 v[26:29], v[156:159], v[196:199], v[26:29]
	v_mfma_f32_16x16x32_bf16 v[14:17], v[148:151], v[204:207], v[14:17]
	v_mfma_f32_16x16x32_bf16 v[10:13], v[156:159], v[204:207], v[10:13]
	s_setprio 0
	s_setprio 1
	v_mfma_f32_16x16x32_bf16 v[54:57], v[160:163], v[176:179], v[54:57]
	v_mfma_f32_16x16x32_bf16 v[50:53], v[168:171], v[176:179], v[50:53]
	v_mfma_f32_16x16x32_bf16 v[38:41], v[160:163], v[184:187], v[38:41]
	v_mfma_f32_16x16x32_bf16 v[34:37], v[168:171], v[184:187], v[34:37]
	v_mfma_f32_16x16x32_bf16 v[22:25], v[160:163], v[192:195], v[22:25]
	v_mfma_f32_16x16x32_bf16 v[18:21], v[168:171], v[192:195], v[18:21]
	v_mfma_f32_16x16x32_bf16 v[6:9], v[160:163], v[200:203], v[6:9]
	v_mfma_f32_16x16x32_bf16 v[2:5], v[168:171], v[200:203], v[2:5]
	s_add_i32 s63, s63, 2
	s_add_u32 s0, s0, 0x100
	s_addc_u32 s1, s1, 0
	s_add_u32 s61, s61, 0x100
	s_addc_u32 s62, s62, 0
	s_add_u32 s6, s0, 0xfffc0080
	s_addc_u32 s7, s1, -1
	s_add_i32 s64, 0, 0x10000
	s_cmp_eq_u32 s63, 12
	s_cselect_b32 s9, s53, s7
	s_cselect_b32 s8, s59, s6
	s_cselect_b32 s7, s51, s62
	s_cselect_b32 s6, s60, s61
	s_add_i32 s66, 0, 0x14000
	s_cmp_gt_u32 s63, 13
	v_mfma_f32_16x16x32_bf16 v[54:57], v[164:167], v[180:183], v[54:57]
	v_mfma_f32_16x16x32_bf16 v[50:53], v[172:175], v[180:183], v[50:53]
	v_mfma_f32_16x16x32_bf16 v[38:41], v[164:167], v[188:191], v[38:41]
	v_mfma_f32_16x16x32_bf16 v[34:37], v[172:175], v[188:191], v[34:37]
	v_mfma_f32_16x16x32_bf16 v[22:25], v[164:167], v[196:199], v[22:25]
	v_mfma_f32_16x16x32_bf16 v[18:21], v[172:175], v[196:199], v[18:21]
	v_mfma_f32_16x16x32_bf16 v[6:9], v[164:167], v[204:207], v[6:9]
	v_mfma_f32_16x16x32_bf16 v[2:5], v[172:175], v[204:207], v[2:5]
	s_setprio 0
	s_barrier
	s_cbranch_scc0 .LBB0_1636
	s_and_b64 vcc, exec, s[48:49]
	s_mov_b64 s[62:63], 0x4000
	s_cbranch_vccz .LBB0_1639
	s_barrier

; #define PG8_STAGE(bufoff, gbase, voff) do { _Pragma("unroll") for (int _i = 0; _i < 2; ++_i) \
;         __builtin_amdgcn_global_load_lds((const unsigned*)((const char*)(gbase) + (voff)[_i]), (PG8_LAS unsigned*)(lds + (bufoff) + ldsw + _i * 8192), 16, 0, 0); } while (0)
; #define PG8_LDA(dst, b, h) do { _Pragma("unroll") for (int m = 0; m < 4; ++m) _Pragma("unroll") for (int k = 0; k < 2; ++k) dst[m][k] = *(const PG8_LAS bf16x8*)(lds + PG8_SA(b, h) + aoff + m * 2048 + k * 1024); } while (0)
; #define PG8_LDB(dst, b, h) do { _Pragma("unroll") for (int n = 0; n < 2; ++n) _Pragma("unroll") for (int k = 0; k < 2; ++k) dst[n][k] = *(const PG8_LAS bf16x8*)(lds + PG8_SB(b, h) + boff + n * 2048 + k * 1024); } while (0)
; #define PG8_WAIT_V(n) asm volatile("s_waitcnt vmcnt(" #n ")" ::: "memory")
; #define PG8_WAIT_L(n) asm volatile("s_waitcnt lgkmcnt(" #n ")" ::: "memory")
; #define PG8_BAR __builtin_amdgcn_s_barrier()
; #define PG8_SCHED __builtin_amdgcn_sched_barrier(0)
; template <class Epi, class Sched, bool ALIGN_EPI = false, bool SP2 = false, bool F16 = false>
; __device__ __forceinline__ void gemm_phase(PG8_LAS unsigned char* lds, const Gemm g, const Sched& S, const Epi& E) {
;     ...
;         const bool has_next = S.next(ui + 1, nxt);
;         const char* nA = has_next ? (const char*)g.A + (size_t)nxt.pm * tstep : cA; const char* nB = has_next ? (const char*)g.Bt + (size_t)nxt.pn * tstep : cB;
;         for (int t = 0; t < nt; t += 2) {
;             const bool last = (t == nt - 2);
;             const char* a1 = cA + (size_t)(t + 1) * kstep;
;             const char* a2 = last ? nA : cA + (size_t)(t + 2) * kstep; const char* b2 = last ? nB : cB + (size_t)(t + 2) * kstep;
;             const char* a3 = a2 + kstep; const char* b3 = b2 + kstep;
;             if (last && has_next) S.a_ready(nxt);
;             if constexpr (SP2) {
;             PG8_LDB(B0, 0, 0); PG8_LDB(B1, 0, 1); PG8_SCHED; PG8_LDA(At, 0, 0); PG8_STAGE(PG8_SA(1, 1), a1 + hstep, voffA);
;             PG8_WAIT_V(8); PG8_WAIT_L(0); PG8_BAR; PG8_MMA(0, 0, At, B0); PG8_MMA(0, 1, At, B1); PG8_BAR; PG8_SCHED;
;             PG8_LDA(At, 0, 1); PG8_STAGE(PG8_SB(0, 0), b2, voffB); PG8_STAGE(PG8_SB(0, 1), b2 + hstep, voffB); PG8_STAGE(PG8_SA(0, 0), a2, voffA);
;             PG8_WAIT_V(8); PG8_WAIT_L(0); PG8_BAR; PG8_MMA(1, 0, At, B0); PG8_MMA(1, 1, At, B1); PG8_BAR; PG8_SCHED;
.LBB0_1709:
	s_add_u32 s67, s18, 0x100
	s_addc_u32 s68, s19, 0
	s_ashr_i32 s13, s12, 31
	s_lshl_b64 s[14:15], s[12:13], 20
	s_add_u32 s16, s54, s14
	s_addc_u32 s17, s55, s15
	s_and_b64 s[14:15], s[42:43], exec
	s_cselect_b32 s13, s17, s1
	s_cselect_b32 s69, s16, s0
	s_ashr_i32 s11, s10, 31
	s_lshl_b64 s[14:15], s[10:11], 20
	s_add_u32 s14, s56, s14
	s_addc_u32 s15, s57, s15
	s_and_b64 s[20:21], s[42:43], exec
	s_cselect_b32 s11, s15, s19
	s_cselect_b32 s70, s14, s18
	s_add_u32 s18, s0, 0x80080
	s_addc_u32 s19, s1, 0
	v_lshl_add_u64 v[140:141], s[18:19], 0, v[136:137]
	v_lshl_add_u64 v[142:143], s[18:19], 0, v[138:139]
	s_mov_b32 s71, -2
	s_mov_b64 s[18:19], 0
	s_add_u32 s20, s0, s18
	s_addc_u32 s21, s1, s19
	s_add_u32 s20, s20, 0x100
	s_addc_u32 s21, s21, 0
	s_add_u32 s72, s67, s18
	s_addc_u32 s73, s68, s19
	s_add_i32 s76, 0, 0x10000
	s_cmpk_eq_i32 s18, 0xf00
	s_cselect_b32 s27, s13, s21
	s_cselect_b32 s26, s69, s20
	s_cselect_b32 s21, s11, s73
	s_cselect_b32 s20, s70, s72
	s_add_i32 s77, 0, 0x14000
.LBB0_1710:
	v_add_u32_e32 v158, s76, v144
	v_add_u32_e32 v174, s77, v144
	ds_read_b128 v[146:149], v158
	ds_read_b128 v[150:153], v158 offset:1024
	ds_read_b128 v[154:157], v158 offset:2048
	ds_read_b128 v[158:161], v158 offset:3072
	ds_read_b128 v[162:165], v174
	ds_read_b128 v[166:169], v174 offset:1024
	ds_read_b128 v[170:173], v174 offset:2048
	ds_read_b128 v[174:177], v174 offset:3072
	v_lshl_add_u64 v[210:211], v[140:141], 0, s[18:19]
	s_add_i32 m0, s59, 0xc000
	ds_read_b128 v[178:181], v145
	ds_read_b128 v[182:185], v145 offset:1024
	ds_read_b128 v[186:189], v145 offset:2048
	ds_read_b128 v[190:193], v145 offset:3072
	ds_read_b128 v[194:197], v145 offset:4096
	ds_read_b128 v[198:201], v145 offset:5120
	ds_read_b128 v[202:205], v145 offset:6144
	ds_read_b128 v[206:209], v145 offset:7168
	global_load_lds_dwordx4 v[210:211], off
	v_lshl_add_u64 v[210:211], v[142:143], 0, s[18:19]
	s_add_i32 m0, s59, 0xe000
	s_nop 0
	global_load_lds_dwordx4 v[210:211], off
	s_waitcnt vmcnt(8)
	s_waitcnt lgkmcnt(0)
	s_barrier
	s_setprio 1
	s_waitcnt lgkmcnt(0)
	v_mfma_f32_16x16x32_bf16 v[126:129], v[146:149], v[178:181], v[126:129]
	v_mfma_f32_16x16x32_bf16 v[122:125], v[154:157], v[178:181], v[122:125]
	v_mfma_f32_16x16x32_bf16 v[110:113], v[146:149], v[186:189], v[110:113]
	v_mfma_f32_16x16x32_bf16 v[106:109], v[154:157], v[186:189], v[106:109]
	v_mfma_f32_16x16x32_bf16 v[94:97], v[146:149], v[194:197], v[94:97]
	v_mfma_f32_16x16x32_bf16 v[90:93], v[154:157], v[194:197], v[90:93]
	v_mfma_f32_16x16x32_bf16 v[78:81], v[146:149], v[202:205], v[78:81]
	v_mfma_f32_16x16x32_bf16 v[74:77], v[154:157], v[202:205], v[74:77]
	v_mfma_f32_16x16x32_bf16 v[126:129], v[150:153], v[182:185], v[126:129]
	v_mfma_f32_16x16x32_bf16 v[122:125], v[158:161], v[182:185], v[122:125]
	v_mfma_f32_16x16x32_bf16 v[110:113], v[150:153], v[190:193], v[110:113]
	v_mfma_f32_16x16x32_bf16 v[106:109], v[158:161], v[190:193], v[106:109]
	v_mfma_f32_16x16x32_bf16 v[94:97], v[150:153], v[198:201], v[94:97]
	v_mfma_f32_16x16x32_bf16 v[90:93], v[158:161], v[198:201], v[90:93]
	v_mfma_f32_16x16x32_bf16 v[78:81], v[150:153], v[206:209], v[78:81]
	v_mfma_f32_16x16x32_bf16 v[74:77], v[158:161], v[206:209], v[74:77]
	s_setprio 0
	s_setprio 1
	v_mfma_f32_16x16x32_bf16 v[118:121], v[162:165], v[178:181], v[118:121]
	v_mfma_f32_16x16x32_bf16 v[114:117], v[170:173], v[178:181], v[114:117]
	v_mfma_f32_16x16x32_bf16 v[102:105], v[162:165], v[186:189], v[102:105]
	v_mfma_f32_16x16x32_bf16 v[98:101], v[170:173], v[186:189], v[98:101]
	v_mfma_f32_16x16x32_bf16 v[86:89], v[162:165], v[194:197], v[86:89]
	v_mfma_f32_16x16x32_bf16 v[82:85], v[170:173], v[194:197], v[82:85]
	v_mfma_f32_16x16x32_bf16 v[70:73], v[162:165], v[202:205], v[70:73]
	v_mfma_f32_16x16x32_bf16 v[66:69], v[170:173], v[202:205], v[66:69]
	v_mfma_f32_16x16x32_bf16 v[118:121], v[166:169], v[182:185], v[118:121]
	v_mfma_f32_16x16x32_bf16 v[114:117], v[174:177], v[182:185], v[114:117]
	v_mfma_f32_16x16x32_bf16 v[102:105], v[166:169], v[190:193], v[102:105]
	v_mfma_f32_16x16x32_bf16 v[98:101], v[174:177], v[190:193], v[98:101]
	v_mfma_f32_16x16x32_bf16 v[86:89], v[166:169], v[198:201], v[86:89]
	v_mfma_f32_16x16x32_bf16 v[82:85], v[174:177], v[198:201], v[82:85]
	v_mfma_f32_16x16x32_bf16 v[70:73], v[166:169], v[206:209], v[70:73]
	v_mfma_f32_16x16x32_bf16 v[66:69], v[174:177], v[206:209], v[66:69]
	s_setprio 0
	s_barrier
	s_add_i32 s72, s76, s58
	v_lshl_add_u64 v[210:211], s[20:21], 0, v[0:1]
	s_mov_b32 m0, s72
	ds_read_b128 v[178:181], v145 offset:16384
	ds_read_b128 v[182:185], v145 offset:17408
	ds_read_b128 v[186:189], v145 offset:18432
	ds_read_b128 v[190:193], v145 offset:19456
	ds_read_b128 v[194:197], v145 offset:20480
	ds_read_b128 v[198:201], v145 offset:21504
	ds_read_b128 v[202:205], v145 offset:22528
	ds_read_b128 v[206:209], v145 offset:23552
	global_load_lds_dwordx4 v[210:211], off
	s_add_i32 m0, s72, 0x2000
	s_add_u32 s72, s20, 0x80000
	v_lshl_add_u64 v[220:221], s[20:21], 0, v[130:131]
	s_addc_u32 s73, s21, 0
	s_add_i32 s76, s77, s58
	global_load_lds_dwordx4 v[220:221], off
	v_lshl_add_u64 v[222:223], s[72:73], 0, v[0:1]
	s_mov_b32 m0, s76
	v_lshl_add_u64 v[224:225], s[26:27], 0, v[132:133]
	global_load_lds_dwordx4 v[222:223], off
	v_lshl_add_u64 v[222:223], s[72:73], 0, v[130:131]
	s_add_i32 m0, s76, 0x2000
	s_nop 0
	global_load_lds_dwordx4 v[222:223], off
	v_lshl_add_u64 v[222:223], s[26:27], 0, v[134:135]
	s_mov_b32 m0, s59
	s_nop 0
	global_load_lds_dwordx4 v[222:223], off
	s_mov_b32 m0, s60
	s_nop 0
	global_load_lds_dwordx4 v[224:225], off
	s_waitcnt vmcnt(8)
	s_waitcnt lgkmcnt(0)
	s_barrier
; #define PG8_STAGE(bufoff, gbase, voff) do { _Pragma("unroll") for (int _i = 0; _i < 2; ++_i) \
;         __builtin_amdgcn_global_load_lds((const unsigned*)((const char*)(gbase) + (voff)[_i]), (PG8_LAS unsigned*)(lds + (bufoff) + ldsw + _i * 8192), 16, 0, 0); } while (0)
; #define PG8_LDA(dst, b, h) do { _Pragma("unroll") for (int m = 0; m < 4; ++m) _Pragma("unroll") for (int k = 0; k < 2; ++k) dst[m][k] = *(const PG8_LAS bf16x8*)(lds + PG8_SA(b, h) + aoff + m * 2048 + k * 1024); } while (0)
; #define PG8_LDB(dst, b, h) do { _Pragma("unroll") for (int n = 0; n < 2; ++n) _Pragma("unroll") for (int k = 0; k < 2; ++k) dst[n][k] = *(const PG8_LAS bf16x8*)(lds + PG8_SB(b, h) + boff + n * 2048 + k * 1024); } while (0)
; #define PG8_MMA(ai, bj, At, Bt) do { __builtin_amdgcn_s_setprio(1); _Pragma("unroll") for (int m = 0; m < 4; ++m) _Pragma("unroll") for (int n = 0; n < 2; ++n) _Pragma("unroll") for (int k = 0; k < 2; ++k) \
;         acc[ai][bj][m][n] = pg8_mma<F16>(Bt[n][k], At[m][k], acc[ai][bj][m][n]); __builtin_amdgcn_s_setprio(0); } while (0)
; #define PG8_WAIT_V(n) asm volatile("s_waitcnt vmcnt(" #n ")" ::: "memory")
; #define PG8_WAIT_L(n) asm volatile("s_waitcnt lgkmcnt(" #n ")" ::: "memory")
; #define PG8_BAR __builtin_amdgcn_s_barrier()
; #define PG8_SCHED __builtin_amdgcn_sched_barrier(0)
; template <class Epi, class Sched, bool ALIGN_EPI = false, bool SP2 = false, bool F16 = false>
; __device__ __forceinline__ void gemm_phase(PG8_LAS unsigned char* lds, const Gemm g, const Sched& S, const Epi& E) {
;     ...
;             PG8_WAIT_V(8); PG8_WAIT_L(0); PG8_BAR; PG8_MMA(1, 0, At, B0); PG8_MMA(1, 1, At, B1); PG8_BAR; PG8_SCHED;
;             PG8_LDB(B0, 1, 0); PG8_LDB(B1, 1, 1); PG8_SCHED; PG8_LDA(At, 1, 0); PG8_STAGE(PG8_SA(0, 1), a2 + hstep, voffA);
;             PG8_WAIT_V(8); PG8_WAIT_L(0); PG8_BAR; PG8_MMA(0, 0, At, B0); PG8_MMA(0, 1, At, B1); PG8_BAR; PG8_SCHED;
	s_setprio 1
	s_waitcnt lgkmcnt(0)
	v_mfma_f32_16x16x32_bf16 v[62:65], v[146:149], v[178:181], v[62:65]
	v_mfma_f32_16x16x32_bf16 v[58:61], v[154:157], v[178:181], v[58:61]
	v_mfma_f32_16x16x32_bf16 v[46:49], v[146:149], v[186:189], v[46:49]
	v_mfma_f32_16x16x32_bf16 v[42:45], v[154:157], v[186:189], v[42:45]
	v_mfma_f32_16x16x32_bf16 v[30:33], v[146:149], v[194:197], v[30:33]
	v_mfma_f32_16x16x32_bf16 v[26:29], v[154:157], v[194:197], v[26:29]
	v_mfma_f32_16x16x32_bf16 v[14:17], v[146:149], v[202:205], v[14:17]
	v_mfma_f32_16x16x32_bf16 v[10:13], v[154:157], v[202:205], v[10:13]
	v_mfma_f32_16x16x32_bf16 v[62:65], v[150:153], v[182:185], v[62:65]
	v_mfma_f32_16x16x32_bf16 v[58:61], v[158:161], v[182:185], v[58:61]
	v_mfma_f32_16x16x32_bf16 v[46:49], v[150:153], v[190:193], v[46:49]
	v_mfma_f32_16x16x32_bf16 v[42:45], v[158:161], v[190:193], v[42:45]
	v_mfma_f32_16x16x32_bf16 v[30:33], v[150:153], v[198:201], v[30:33]
	v_mfma_f32_16x16x32_bf16 v[26:29], v[158:161], v[198:201], v[26:29]
	v_mfma_f32_16x16x32_bf16 v[14:17], v[150:153], v[206:209], v[14:17]
	v_mfma_f32_16x16x32_bf16 v[10:13], v[158:161], v[206:209], v[10:13]
	s_setprio 0
	s_setprio 1
	v_mfma_f32_16x16x32_bf16 v[54:57], v[162:165], v[178:181], v[54:57]
	v_mfma_f32_16x16x32_bf16 v[50:53], v[170:173], v[178:181], v[50:53]
	v_mfma_f32_16x16x32_bf16 v[38:41], v[162:165], v[186:189], v[38:41]
	v_mfma_f32_16x16x32_bf16 v[34:37], v[170:173], v[186:189], v[34:37]
	v_mfma_f32_16x16x32_bf16 v[22:25], v[162:165], v[194:197], v[22:25]
	v_mfma_f32_16x16x32_bf16 v[18:21], v[170:173], v[194:197], v[18:21]
	v_mfma_f32_16x16x32_bf16 v[6:9], v[162:165], v[202:205], v[6:9]
	v_mfma_f32_16x16x32_bf16 v[2:5], v[170:173], v[202:205], v[2:5]
	v_mfma_f32_16x16x32_bf16 v[54:57], v[166:169], v[182:185], v[54:57]
	v_mfma_f32_16x16x32_bf16 v[50:53], v[174:177], v[182:185], v[50:53]
	v_mfma_f32_16x16x32_bf16 v[38:41], v[166:169], v[190:193], v[38:41]
	v_mfma_f32_16x16x32_bf16 v[34:37], v[174:177], v[190:193], v[34:37]
	v_mfma_f32_16x16x32_bf16 v[22:25], v[166:169], v[198:201], v[22:25]
	v_mfma_f32_16x16x32_bf16 v[18:21], v[174:177], v[198:201], v[18:21]
	v_mfma_f32_16x16x32_bf16 v[6:9], v[166:169], v[206:209], v[6:9]
	v_mfma_f32_16x16x32_bf16 v[2:5], v[174:177], v[206:209], v[2:5]
	s_setprio 0
	s_barrier
	s_add_i32 s72, 0, 0x18000
	s_add_i32 s73, 0, 0x1c000
	v_add_u32_e32 v158, s72, v144
	v_add_u32_e32 v174, s73, v144
	ds_read_b128 v[146:149], v158
	ds_read_b128 v[150:153], v158 offset:1024
	ds_read_b128 v[154:157], v158 offset:2048
	ds_read_b128 v[158:161], v158 offset:3072
	ds_read_b128 v[162:165], v174
	ds_read_b128 v[166:169], v174 offset:1024
	ds_read_b128 v[170:173], v174 offset:2048
	ds_read_b128 v[174:177], v174 offset:3072
	s_add_u32 s26, s26, 0x80000
	s_addc_u32 s27, s27, 0
	s_mov_b32 m0, s61
	v_lshl_add_u64 v[226:227], s[26:27], 0, v[134:135]
	ds_read_b128 v[178:181], v145 offset:32768
	ds_read_b128 v[182:185], v145 offset:33792
	ds_read_b128 v[186:189], v145 offset:34816
	ds_read_b128 v[190:193], v145 offset:35840
	ds_read_b128 v[194:197], v145 offset:36864
	ds_read_b128 v[198:201], v145 offset:37888
	ds_read_b128 v[202:205], v145 offset:38912
	ds_read_b128 v[206:209], v145 offset:39936
	global_load_lds_dwordx4 v[226:227], off
	v_lshl_add_u64 v[226:227], s[26:27], 0, v[132:133]
	s_mov_b32 m0, s62
	s_nop 0
	global_load_lds_dwordx4 v[226:227], off
	s_waitcnt vmcnt(8)
	s_waitcnt lgkmcnt(0)
	s_barrier
	s_setprio 1
	s_waitcnt lgkmcnt(0)
	v_mfma_f32_16x16x32_bf16 v[126:129], v[146:149], v[178:181], v[126:129]
	v_mfma_f32_16x16x32_bf16 v[122:125], v[154:157], v[178:181], v[122:125]
	v_mfma_f32_16x16x32_bf16 v[110:113], v[146:149], v[186:189], v[110:113]
	v_mfma_f32_16x16x32_bf16 v[106:109], v[154:157], v[186:189], v[106:109]
	v_mfma_f32_16x16x32_bf16 v[94:97], v[146:149], v[194:197], v[94:97]
	v_mfma_f32_16x16x32_bf16 v[90:93], v[154:157], v[194:197], v[90:93]
	v_mfma_f32_16x16x32_bf16 v[78:81], v[146:149], v[202:205], v[78:81]
	v_mfma_f32_16x16x32_bf16 v[74:77], v[154:157], v[202:205], v[74:77]
	v_mfma_f32_16x16x32_bf16 v[126:129], v[150:153], v[182:185], v[126:129]
	v_mfma_f32_16x16x32_bf16 v[122:125], v[158:161], v[182:185], v[122:125]
	v_mfma_f32_16x16x32_bf16 v[110:113], v[150:153], v[190:193], v[110:113]
	v_mfma_f32_16x16x32_bf16 v[106:109], v[158:161], v[190:193], v[106:109]
	v_mfma_f32_16x16x32_bf16 v[94:97], v[150:153], v[198:201], v[94:97]
	v_mfma_f32_16x16x32_bf16 v[90:93], v[158:161], v[198:201], v[90:93]
	v_mfma_f32_16x16x32_bf16 v[78:81], v[150:153], v[206:209], v[78:81]
	v_mfma_f32_16x16x32_bf16 v[74:77], v[158:161], v[206:209], v[74:77]
	s_setprio 0
	s_setprio 1
	v_mfma_f32_16x16x32_bf16 v[118:121], v[162:165], v[178:181], v[118:121]
	v_mfma_f32_16x16x32_bf16 v[114:117], v[170:173], v[178:181], v[114:117]
	v_mfma_f32_16x16x32_bf16 v[102:105], v[162:165], v[186:189], v[102:105]
	v_mfma_f32_16x16x32_bf16 v[98:101], v[170:173], v[186:189], v[98:101]
	v_mfma_f32_16x16x32_bf16 v[86:89], v[162:165], v[194:197], v[86:89]
	v_mfma_f32_16x16x32_bf16 v[82:85], v[170:173], v[194:197], v[82:85]
	v_mfma_f32_16x16x32_bf16 v[70:73], v[162:165], v[202:205], v[70:73]
	v_mfma_f32_16x16x32_bf16 v[66:69], v[170:173], v[202:205], v[66:69]
	v_mfma_f32_16x16x32_bf16 v[118:121], v[166:169], v[182:185], v[118:121]
	v_mfma_f32_16x16x32_bf16 v[114:117], v[174:177], v[182:185], v[114:117]
	v_mfma_f32_16x16x32_bf16 v[102:105], v[166:169], v[190:193], v[102:105]
	v_mfma_f32_16x16x32_bf16 v[98:101], v[174:177], v[190:193], v[98:101]
	v_mfma_f32_16x16x32_bf16 v[86:89], v[166:169], v[198:201], v[86:89]
	v_mfma_f32_16x16x32_bf16 v[82:85], v[174:177], v[198:201], v[82:85]
	v_mfma_f32_16x16x32_bf16 v[70:73], v[166:169], v[206:209], v[70:73]
	v_mfma_f32_16x16x32_bf16 v[66:69], v[174:177], v[206:209], v[66:69]
	s_setprio 0
	s_barrier
; #define PG8_STAGE(bufoff, gbase, voff) do { _Pragma("unroll") for (int _i = 0; _i < 2; ++_i) \
;         __builtin_amdgcn_global_load_lds((const unsigned*)((const char*)(gbase) + (voff)[_i]), (PG8_LAS unsigned*)(lds + (bufoff) + ldsw + _i * 8192), 16, 0, 0); } while (0)
; #define PG8_LDA(dst, b, h) do { _Pragma("unroll") for (int m = 0; m < 4; ++m) _Pragma("unroll") for (int k = 0; k < 2; ++k) dst[m][k] = *(const PG8_LAS bf16x8*)(lds + PG8_SA(b, h) + aoff + m * 2048 + k * 1024); } while (0)
; #define PG8_MMA(ai, bj, At, Bt) do { __builtin_amdgcn_s_setprio(1); _Pragma("unroll") for (int m = 0; m < 4; ++m) _Pragma("unroll") for (int n = 0; n < 2; ++n) _Pragma("unroll") for (int k = 0; k < 2; ++k) \
;         acc[ai][bj][m][n] = pg8_mma<F16>(Bt[n][k], At[m][k], acc[ai][bj][m][n]); __builtin_amdgcn_s_setprio(0); } while (0)
; #define PG8_WAIT_V(n) asm volatile("s_waitcnt vmcnt(" #n ")" ::: "memory")
; #define PG8_WAIT_L(n) asm volatile("s_waitcnt lgkmcnt(" #n ")" ::: "memory")
; #define PG8_BAR __builtin_amdgcn_s_barrier()
; #define PG8_SCHED __builtin_amdgcn_sched_barrier(0)
; template <class Epi, class Sched, bool ALIGN_EPI = false, bool SP2 = false, bool F16 = false>
; __device__ __forceinline__ void gemm_phase(PG8_LAS unsigned char* lds, const Gemm g, const Sched& S, const Epi& E) {
;     ...
;         for (int t = 0; t < nt; t += 2) {
;             const bool last = (t == nt - 2);
;             const char* a1 = cA + (size_t)(t + 1) * kstep;
;             const char* a2 = last ? nA : cA + (size_t)(t + 2) * kstep; const char* b2 = last ? nB : cB + (size_t)(t + 2) * kstep;
;             const char* a3 = a2 + kstep; const char* b3 = b2 + kstep;
;     ...
;             PG8_WAIT_V(8); PG8_WAIT_L(0); PG8_BAR; PG8_MMA(0, 0, At, B0); PG8_MMA(0, 1, At, B1); PG8_BAR; PG8_SCHED;
;             PG8_LDA(At, 1, 1); PG8_STAGE(PG8_SB(1, 0), b3, voffB); PG8_STAGE(PG8_SB(1, 1), b3 + hstep, voffB); PG8_STAGE(PG8_SA(1, 0), a3, voffA);
;             PG8_WAIT_V(8); PG8_WAIT_L(0); PG8_BAR; PG8_MMA(1, 0, At, B0); PG8_MMA(1, 1, At, B1); PG8_BAR; PG8_SCHED;
	s_add_i32 s26, s72, s58
	v_lshl_add_u64 v[210:211], v[210:211], 0, s[24:25]
	s_mov_b32 m0, s26
	ds_read_b128 v[178:181], v145 offset:49152
	ds_read_b128 v[182:185], v145 offset:50176
	ds_read_b128 v[186:189], v145 offset:51200
	ds_read_b128 v[190:193], v145 offset:52224
	ds_read_b128 v[194:197], v145 offset:53248
	ds_read_b128 v[198:201], v145 offset:54272
	ds_read_b128 v[202:205], v145 offset:55296
	ds_read_b128 v[206:209], v145 offset:56320
	global_load_lds_dwordx4 v[210:211], off
	s_add_i32 m0, s26, 0x2000
	s_add_u32 s20, s20, 0x80080
	v_lshl_add_u64 v[210:211], v[220:221], 0, s[24:25]
	s_addc_u32 s21, s21, 0
	s_add_i32 s26, s73, s58
	global_load_lds_dwordx4 v[210:211], off
	v_lshl_add_u64 v[210:211], s[20:21], 0, v[0:1]
	s_mov_b32 m0, s26
	s_nop 0
	global_load_lds_dwordx4 v[210:211], off
	v_lshl_add_u64 v[210:211], s[20:21], 0, v[130:131]
	s_add_i32 m0, s26, 0x2000
	s_nop 0
	global_load_lds_dwordx4 v[210:211], off
	v_lshl_add_u64 v[210:211], v[222:223], 0, s[24:25]
	s_mov_b32 m0, s63
	s_nop 0
	global_load_lds_dwordx4 v[210:211], off
	v_lshl_add_u64 v[210:211], v[224:225], 0, s[24:25]
	s_mov_b32 m0, s64
	s_nop 0
	global_load_lds_dwordx4 v[210:211], off
	s_waitcnt vmcnt(8)
	s_waitcnt lgkmcnt(0)
	s_barrier
	s_setprio 1
	s_waitcnt lgkmcnt(0)
	v_mfma_f32_16x16x32_bf16 v[62:65], v[146:149], v[178:181], v[62:65]
	v_mfma_f32_16x16x32_bf16 v[58:61], v[154:157], v[178:181], v[58:61]
	v_mfma_f32_16x16x32_bf16 v[46:49], v[146:149], v[186:189], v[46:49]
	v_mfma_f32_16x16x32_bf16 v[42:45], v[154:157], v[186:189], v[42:45]
	v_mfma_f32_16x16x32_bf16 v[30:33], v[146:149], v[194:197], v[30:33]
	v_mfma_f32_16x16x32_bf16 v[26:29], v[154:157], v[194:197], v[26:29]
	v_mfma_f32_16x16x32_bf16 v[14:17], v[146:149], v[202:205], v[14:17]
	v_mfma_f32_16x16x32_bf16 v[10:13], v[154:157], v[202:205], v[10:13]
	v_mfma_f32_16x16x32_bf16 v[62:65], v[150:153], v[182:185], v[62:65]
	v_mfma_f32_16x16x32_bf16 v[58:61], v[158:161], v[182:185], v[58:61]
	v_mfma_f32_16x16x32_bf16 v[46:49], v[150:153], v[190:193], v[46:49]
	v_mfma_f32_16x16x32_bf16 v[42:45], v[158:161], v[190:193], v[42:45]
	v_mfma_f32_16x16x32_bf16 v[30:33], v[150:153], v[198:201], v[30:33]
	v_mfma_f32_16x16x32_bf16 v[26:29], v[158:161], v[198:201], v[26:29]
	v_mfma_f32_16x16x32_bf16 v[14:17], v[150:153], v[206:209], v[14:17]
	v_mfma_f32_16x16x32_bf16 v[10:13], v[158:161], v[206:209], v[10:13]
	s_setprio 0
	s_setprio 1
	v_mfma_f32_16x16x32_bf16 v[54:57], v[162:165], v[178:181], v[54:57]
	v_mfma_f32_16x16x32_bf16 v[50:53], v[170:173], v[178:181], v[50:53]
	v_mfma_f32_16x16x32_bf16 v[38:41], v[162:165], v[186:189], v[38:41]
	v_mfma_f32_16x16x32_bf16 v[34:37], v[170:173], v[186:189], v[34:37]
	v_mfma_f32_16x16x32_bf16 v[22:25], v[162:165], v[194:197], v[22:25]
	v_mfma_f32_16x16x32_bf16 v[18:21], v[170:173], v[194:197], v[18:21]
	v_mfma_f32_16x16x32_bf16 v[6:9], v[162:165], v[202:205], v[6:9]
	v_mfma_f32_16x16x32_bf16 v[2:5], v[170:173], v[202:205], v[2:5]
	s_add_i32 s71, s71, 2
	s_add_u32 s18, s18, 0x100
	s_addc_u32 s19, s19, 0
	s_add_u32 s20, s0, s18
	s_addc_u32 s21, s1, s19
	s_add_u32 s20, s20, 0x100
	s_addc_u32 s21, s21, 0
	s_add_u32 s72, s67, s18
	s_addc_u32 s73, s68, s19
	s_add_i32 s76, 0, 0x10000
	s_cmpk_eq_i32 s18, 0xf00
	s_cselect_b32 s27, s13, s21
	s_cselect_b32 s26, s69, s20
	s_cselect_b32 s21, s11, s73
	s_cselect_b32 s20, s70, s72
	s_add_i32 s77, 0, 0x14000
	s_cmp_gt_u32 s71, 29
	v_mfma_f32_16x16x32_bf16 v[54:57], v[166:169], v[182:185], v[54:57]
	v_mfma_f32_16x16x32_bf16 v[50:53], v[174:177], v[182:185], v[50:53]
	v_mfma_f32_16x16x32_bf16 v[38:41], v[166:169], v[190:193], v[38:41]
	v_mfma_f32_16x16x32_bf16 v[34:37], v[174:177], v[190:193], v[34:37]
	v_mfma_f32_16x16x32_bf16 v[22:25], v[166:169], v[198:201], v[22:25]
	v_mfma_f32_16x16x32_bf16 v[18:21], v[174:177], v[198:201], v[18:21]
	v_mfma_f32_16x16x32_bf16 v[6:9], v[166:169], v[206:209], v[6:9]
	v_mfma_f32_16x16x32_bf16 v[2:5], v[174:177], v[206:209], v[2:5]
	s_setprio 0
	s_barrier
; #define PG8_BAR __builtin_amdgcn_s_barrier()
; template <class Epi, class Sched, bool ALIGN_EPI = false, bool SP2 = false, bool F16 = false>
; __device__ __forceinline__ void gemm_phase(PG8_LAS unsigned char* lds, const Gemm g, const Sched& S, const Epi& E) {
;     ...
;         if constexpr (ALIGN_EPI) { if (wr == 0) PG8_BAR; }
;         if constexpr (!Epi::AFTER_DRAIN) { E(acc, cur, wr, wc, fr, fq); S.done(cur); }
;         if (!has_next) break;
; #pragma unroll
;         for (int a = 0; a < 2; ++a)
; #pragma unroll
;             for (int b = 0; b < 2; ++b)
; #pragma unroll
;                 for (int m = 0; m < 4; ++m)
; #pragma unroll
;                     for (int n = 0; n < 2; ++n) acc[a][b][m][n] = (f32x4){0.f, 0.f, 0.f, 0.f};
;         cur = nxt; cA = nA; cB = nB; ++ui;
;         if constexpr (ALIGN_EPI) { if (wr == 1) PG8_BAR; }
	s_cbranch_scc0 .LBB0_1710
	s_add_u32 s18, s67, 0xffffff00
	s_addc_u32 s19, s68, -1
	s_andn2_b64 vcc, exec, s[42:43]
	s_cbranch_vccnz .LBB0_1701
	v_mov_b32_e32 v2, 0
	s_mov_b32 s8, s10
	s_mov_b32 s47, s12
	s_mov_b64 s[0:1], s[16:17]
	s_mov_b32 s65, s66
	v_mov_b32_e32 v3, v2
	v_mov_b32_e32 v4, v2
	v_mov_b32_e32 v5, v2
	v_mov_b32_e32 v6, v2
	v_mov_b32_e32 v7, v2
	v_mov_b32_e32 v8, v2
	v_mov_b32_e32 v9, v2
	v_mov_b32_e32 v18, v2
	v_mov_b32_e32 v19, v2
	v_mov_b32_e32 v20, v2
	v_mov_b32_e32 v21, v2
	v_mov_b32_e32 v22, v2
	v_mov_b32_e32 v23, v2
	v_mov_b32_e32 v24, v2
	v_mov_b32_e32 v25, v2
	v_mov_b32_e32 v34, v2
	v_mov_b32_e32 v35, v2
	v_mov_b32_e32 v36, v2
	v_mov_b32_e32 v37, v2
	v_mov_b32_e32 v38, v2
	v_mov_b32_e32 v39, v2
	v_mov_b32_e32 v40, v2
	v_mov_b32_e32 v41, v2
	v_mov_b32_e32 v50, v2
	v_mov_b32_e32 v51, v2
	v_mov_b32_e32 v52, v2
	v_mov_b32_e32 v53, v2
	v_mov_b32_e32 v54, v2
	v_mov_b32_e32 v55, v2
	v_mov_b32_e32 v56, v2
	v_mov_b32_e32 v57, v2
	v_mov_b32_e32 v10, v2
	v_mov_b32_e32 v11, v2
	v_mov_b32_e32 v12, v2
	v_mov_b32_e32 v13, v2
	v_mov_b32_e32 v14, v2
	v_mov_b32_e32 v15, v2
	v_mov_b32_e32 v16, v2
	v_mov_b32_e32 v17, v2
	v_mov_b32_e32 v26, v2
	v_mov_b32_e32 v27, v2
	v_mov_b32_e32 v28, v2
	v_mov_b32_e32 v29, v2
	v_mov_b32_e32 v30, v2
	v_mov_b32_e32 v31, v2
	v_mov_b32_e32 v32, v2
	v_mov_b32_e32 v33, v2
	v_mov_b32_e32 v42, v2
	v_mov_b32_e32 v43, v2
	v_mov_b32_e32 v44, v2
	v_mov_b32_e32 v45, v2
	v_mov_b32_e32 v46, v2
	v_mov_b32_e32 v47, v2
	v_mov_b32_e32 v48, v2
	v_mov_b32_e32 v49, v2
	v_mov_b32_e32 v58, v2
	v_mov_b32_e32 v59, v2
	v_mov_b32_e32 v60, v2
	v_mov_b32_e32 v61, v2
	v_mov_b32_e32 v62, v2
	v_mov_b32_e32 v63, v2
	v_mov_b32_e32 v64, v2
	v_mov_b32_e32 v65, v2
	v_mov_b32_e32 v66, v2
	v_mov_b32_e32 v67, v2
	v_mov_b32_e32 v68, v2
	v_mov_b32_e32 v69, v2
	v_mov_b32_e32 v70, v2
	v_mov_b32_e32 v71, v2
	v_mov_b32_e32 v72, v2
	v_mov_b32_e32 v73, v2
	v_mov_b32_e32 v82, v2
	v_mov_b32_e32 v83, v2
	v_mov_b32_e32 v84, v2
	v_mov_b32_e32 v85, v2
	v_mov_b32_e32 v86, v2
	v_mov_b32_e32 v87, v2
	v_mov_b32_e32 v88, v2
	v_mov_b32_e32 v89, v2
	v_mov_b32_e32 v98, v2
	v_mov_b32_e32 v99, v2
	v_mov_b32_e32 v100, v2
	v_mov_b32_e32 v101, v2
	v_mov_b32_e32 v102, v2
	v_mov_b32_e32 v103, v2
	v_mov_b32_e32 v104, v2
	v_mov_b32_e32 v105, v2
	v_mov_b32_e32 v114, v2
	v_mov_b32_e32 v115, v2
	v_mov_b32_e32 v116, v2
	v_mov_b32_e32 v117, v2
	v_mov_b32_e32 v118, v2
	v_mov_b32_e32 v119, v2
	v_mov_b32_e32 v120, v2
	v_mov_b32_e32 v121, v2
	v_mov_b32_e32 v74, v2
	v_mov_b32_e32 v75, v2
	v_mov_b32_e32 v76, v2
	v_mov_b32_e32 v77, v2
	v_mov_b32_e32 v78, v2
	v_mov_b32_e32 v79, v2
	v_mov_b32_e32 v80, v2
	v_mov_b32_e32 v81, v2
	v_mov_b32_e32 v90, v2
	v_mov_b32_e32 v91, v2
	v_mov_b32_e32 v92, v2
	v_mov_b32_e32 v93, v2
	v_mov_b32_e32 v94, v2
	v_mov_b32_e32 v95, v2
	v_mov_b32_e32 v96, v2
	v_mov_b32_e32 v97, v2
	v_mov_b32_e32 v106, v2
	v_mov_b32_e32 v107, v2
	v_mov_b32_e32 v108, v2
	v_mov_b32_e32 v109, v2
	v_mov_b32_e32 v110, v2
	v_mov_b32_e32 v111, v2
	v_mov_b32_e32 v112, v2
	v_mov_b32_e32 v113, v2
	v_mov_b32_e32 v122, v2
	v_mov_b32_e32 v123, v2
	v_mov_b32_e32 v124, v2
	v_mov_b32_e32 v125, v2
	v_mov_b32_e32 v126, v2
	v_mov_b32_e32 v127, v2
	v_mov_b32_e32 v128, v2
	v_mov_b32_e32 v129, v2
	s_movk_i32 s77, 0xfff
	s_andn2_b64 vcc, exec, s[40:41]
	s_cbranch_vccnz .LBB0_1702

; #define PG8_STAGE(bufoff, gbase, voff) do { _Pragma("unroll") for (int _i = 0; _i < 2; ++_i) \
;         __builtin_amdgcn_global_load_lds((const unsigned*)((const char*)(gbase) + (voff)[_i]), (PG8_LAS unsigned*)(lds + (bufoff) + ldsw + _i * 8192), 16, 0, 0); } while (0)
; #define PG8_LDA(dst, b, h) do { _Pragma("unroll") for (int m = 0; m < 4; ++m) _Pragma("unroll") for (int k = 0; k < 2; ++k) dst[m][k] = *(const PG8_LAS bf16x8*)(lds + PG8_SA(b, h) + aoff + m * 2048 + k * 1024); } while (0)
; #define PG8_LDB(dst, b, h) do { _Pragma("unroll") for (int n = 0; n < 2; ++n) _Pragma("unroll") for (int k = 0; k < 2; ++k) dst[n][k] = *(const PG8_LAS bf16x8*)(lds + PG8_SB(b, h) + boff + n * 2048 + k * 1024); } while (0)
; #define PG8_SCHED __builtin_amdgcn_sched_barrier(0)
; template <class Epi, class Sched, bool ALIGN_EPI = false, bool SP2 = false, bool F16 = false>
; __device__ __forceinline__ void gemm_phase(PG8_LAS unsigned char* lds, const Gemm g, const Sched& S, const Epi& E) {
;     ...
;         const bool has_next = S.next(ui + 1, nxt);
;         const char* nA = has_next ? (const char*)g.A + (size_t)nxt.pm * tstep : cA; const char* nB = has_next ? (const char*)g.Bt + (size_t)nxt.pn * tstep : cB;
;         for (int t = 0; t < nt; t += 2) {
;             const bool last = (t == nt - 2);
;             const char* a1 = cA + (size_t)(t + 1) * kstep;
;             const char* a2 = last ? nA : cA + (size_t)(t + 2) * kstep; const char* b2 = last ? nB : cB + (size_t)(t + 2) * kstep;
;             const char* a3 = a2 + kstep; const char* b3 = b2 + kstep;
;             if (last && has_next) S.a_ready(nxt);
;             if constexpr (SP2) {
;             PG8_LDB(B0, 0, 0); PG8_LDB(B1, 0, 1); PG8_SCHED; PG8_LDA(At, 0, 0); PG8_STAGE(PG8_SA(1, 1), a1 + hstep, voffA);
;     ...
; #pragma unroll
;         for (int a = 0; a < 2; ++a)
; #pragma unroll
;             for (int b = 0; b < 2; ++b)
; #pragma unroll
;                 for (int m = 0; m < 4; ++m)
; #pragma unroll
;                     for (int n = 0; n < 2; ++n) acc[a][b][m][n] = (f32x4){0.f, 0.f, 0.f, 0.f};
.LBB0_1815:
	s_ashr_i32 s17, s16, 31
	s_lshl_b64 s[18:19], s[16:17], 20
	s_add_u32 s18, s48, s18
	s_addc_u32 s19, s49, s19
	s_and_b64 s[20:21], s[40:41], exec
	s_cselect_b32 s17, s19, s27
	s_cselect_b32 s64, s18, s26
	s_ashr_i32 s15, s14, 31
	s_lshl_b64 s[20:21], s[14:15], 20
	s_add_u32 s20, s50, s20
	s_addc_u32 s21, s51, s21
	s_and_b64 s[44:45], s[40:41], exec
	s_cselect_b32 s15, s21, s43
	s_cselect_b32 s65, s20, s42
	s_add_u32 s26, s26, 0x80080
	s_addc_u32 s27, s27, 0
	s_add_u32 s66, s42, 0x100
	v_mov_b32_e32 v2, 0
	s_addc_u32 s67, s43, 0
	s_mov_b32 s68, -2
	v_mov_b32_e32 v3, v2
	v_mov_b32_e32 v4, v2
	v_mov_b32_e32 v5, v2
	v_mov_b32_e32 v6, v2
	v_mov_b32_e32 v7, v2
	v_mov_b32_e32 v8, v2
	v_mov_b32_e32 v9, v2
	v_mov_b32_e32 v18, v2
	v_mov_b32_e32 v19, v2
	v_mov_b32_e32 v20, v2
	v_mov_b32_e32 v21, v2
	v_mov_b32_e32 v22, v2
	v_mov_b32_e32 v23, v2
	v_mov_b32_e32 v24, v2
	v_mov_b32_e32 v25, v2
	v_mov_b32_e32 v34, v2
	v_mov_b32_e32 v35, v2
	v_mov_b32_e32 v36, v2
	v_mov_b32_e32 v37, v2
	v_mov_b32_e32 v38, v2
	v_mov_b32_e32 v39, v2
	v_mov_b32_e32 v40, v2
	v_mov_b32_e32 v41, v2
	v_mov_b32_e32 v50, v2
	v_mov_b32_e32 v51, v2
	v_mov_b32_e32 v52, v2
	v_mov_b32_e32 v53, v2
	v_mov_b32_e32 v54, v2
	v_mov_b32_e32 v55, v2
	v_mov_b32_e32 v56, v2
	v_mov_b32_e32 v57, v2
	v_mov_b32_e32 v10, v2
	v_mov_b32_e32 v11, v2
	v_mov_b32_e32 v12, v2
	v_mov_b32_e32 v13, v2
	v_mov_b32_e32 v14, v2
	v_mov_b32_e32 v15, v2
	v_mov_b32_e32 v16, v2
	v_mov_b32_e32 v17, v2
	v_mov_b32_e32 v26, v2
	v_mov_b32_e32 v27, v2
	v_mov_b32_e32 v28, v2
	v_mov_b32_e32 v29, v2
	v_mov_b32_e32 v30, v2
	v_mov_b32_e32 v31, v2
	v_mov_b32_e32 v32, v2
	v_mov_b32_e32 v33, v2
	v_mov_b32_e32 v42, v2
	v_mov_b32_e32 v43, v2
	v_mov_b32_e32 v44, v2
	v_mov_b32_e32 v45, v2
	v_mov_b32_e32 v46, v2
	v_mov_b32_e32 v47, v2
	v_mov_b32_e32 v48, v2
	v_mov_b32_e32 v49, v2
	v_mov_b32_e32 v58, v2
	v_mov_b32_e32 v59, v2
	v_mov_b32_e32 v60, v2
	v_mov_b32_e32 v61, v2
	v_mov_b32_e32 v62, v2
	v_mov_b32_e32 v63, v2
	v_mov_b32_e32 v64, v2
	v_mov_b32_e32 v65, v2
	v_mov_b32_e32 v66, v2
	v_mov_b32_e32 v67, v2
	v_mov_b32_e32 v68, v2
	v_mov_b32_e32 v69, v2
	v_mov_b32_e32 v70, v2
	v_mov_b32_e32 v71, v2
	v_mov_b32_e32 v72, v2
	v_mov_b32_e32 v73, v2
	v_mov_b32_e32 v82, v2
	v_mov_b32_e32 v83, v2
	v_mov_b32_e32 v84, v2
	v_mov_b32_e32 v85, v2
	v_mov_b32_e32 v86, v2
	v_mov_b32_e32 v87, v2
	v_mov_b32_e32 v88, v2
	v_mov_b32_e32 v89, v2
	v_mov_b32_e32 v98, v2
	v_mov_b32_e32 v99, v2
	v_mov_b32_e32 v100, v2
	v_mov_b32_e32 v101, v2
	v_mov_b32_e32 v102, v2
	v_mov_b32_e32 v103, v2
	v_mov_b32_e32 v104, v2
	v_mov_b32_e32 v105, v2
	v_mov_b32_e32 v114, v2
	v_mov_b32_e32 v115, v2
	v_mov_b32_e32 v116, v2
	v_mov_b32_e32 v117, v2
	v_mov_b32_e32 v118, v2
	v_mov_b32_e32 v119, v2
	v_mov_b32_e32 v120, v2
	v_mov_b32_e32 v121, v2
	v_mov_b32_e32 v74, v2
	v_mov_b32_e32 v75, v2
	v_mov_b32_e32 v76, v2
	v_mov_b32_e32 v77, v2
	v_mov_b32_e32 v78, v2
	v_mov_b32_e32 v79, v2
	v_mov_b32_e32 v80, v2
	v_mov_b32_e32 v81, v2
	v_mov_b32_e32 v90, v2
	v_mov_b32_e32 v91, v2
	v_mov_b32_e32 v92, v2
	v_mov_b32_e32 v93, v2
	v_mov_b32_e32 v94, v2
	v_mov_b32_e32 v95, v2
	v_mov_b32_e32 v96, v2
	v_mov_b32_e32 v97, v2
	v_mov_b32_e32 v106, v2
	v_mov_b32_e32 v107, v2
	v_mov_b32_e32 v108, v2
	v_mov_b32_e32 v109, v2
	v_mov_b32_e32 v110, v2
	v_mov_b32_e32 v111, v2
	v_mov_b32_e32 v112, v2
	v_mov_b32_e32 v113, v2
	v_mov_b32_e32 v122, v2
	v_mov_b32_e32 v123, v2
	v_mov_b32_e32 v124, v2
	v_mov_b32_e32 v125, v2
	v_mov_b32_e32 v126, v2
	v_mov_b32_e32 v127, v2
	v_mov_b32_e32 v128, v2
	v_mov_b32_e32 v129, v2
	s_add_u32 s42, s26, 0xfff80080
	s_addc_u32 s43, s27, -1
	s_add_i32 s69, 0, 0x10000
	s_cmp_eq_u32 s68, 28
	s_cselect_b32 s45, s17, s43
	s_cselect_b32 s44, s64, s42
	s_cselect_b32 s43, s15, s67
	s_cselect_b32 s42, s65, s66
	s_add_i32 s72, 0, 0x14000
.LBB0_1816:
	v_add_u32_e32 v140, s69, v143
	ds_read_b128 v[146:149], v140
	ds_read_b128 v[150:153], v140 offset:1024
	ds_read_b128 v[154:157], v140 offset:2048
	ds_read_b128 v[158:161], v140 offset:3072
	v_add_u32_e32 v140, s72, v143
	ds_read_b128 v[162:165], v140
	ds_read_b128 v[166:169], v140 offset:1024
	ds_read_b128 v[170:173], v140 offset:2048
	ds_read_b128 v[174:177], v140 offset:3072
	v_lshl_add_u64 v[140:141], s[26:27], 0, v[136:137]
	s_add_i32 m0, s54, 0xc000
	ds_read_b128 v[178:181], v145
	ds_read_b128 v[182:185], v145 offset:1024
	ds_read_b128 v[186:189], v145 offset:2048
	ds_read_b128 v[190:193], v145 offset:3072
	ds_read_b128 v[194:197], v145 offset:4096
	ds_read_b128 v[198:201], v145 offset:5120
	ds_read_b128 v[202:205], v145 offset:6144
	ds_read_b128 v[206:209], v145 offset:7168
	global_load_lds_dwordx4 v[140:141], off
	v_lshl_add_u64 v[140:141], s[26:27], 0, v[138:139]
	s_add_i32 m0, s54, 0xe000
	s_nop 0
	global_load_lds_dwordx4 v[140:141], off
	s_cmp_eq_u32 s100, 0
	s_cbranch_scc1 .Lur_up_n0
	s_sub_u32 s100, s100, 1
	s_waitcnt vmcnt(16)
	s_branch .Lur_up_d0

; #define PG8_STAGE(bufoff, gbase, voff) do { _Pragma("unroll") for (int _i = 0; _i < 2; ++_i) \
;         __builtin_amdgcn_global_load_lds((const unsigned*)((const char*)(gbase) + (voff)[_i]), (PG8_LAS unsigned*)(lds + (bufoff) + ldsw + _i * 8192), 16, 0, 0); } while (0)
; #define PG8_LDA(dst, b, h) do { _Pragma("unroll") for (int m = 0; m < 4; ++m) _Pragma("unroll") for (int k = 0; k < 2; ++k) dst[m][k] = *(const PG8_LAS bf16x8*)(lds + PG8_SA(b, h) + aoff + m * 2048 + k * 1024); } while (0)
; #define PG8_LDB(dst, b, h) do { _Pragma("unroll") for (int n = 0; n < 2; ++n) _Pragma("unroll") for (int k = 0; k < 2; ++k) dst[n][k] = *(const PG8_LAS bf16x8*)(lds + PG8_SB(b, h) + boff + n * 2048 + k * 1024); } while (0)
; #define PG8_MMA(ai, bj, At, Bt) do { __builtin_amdgcn_s_setprio(1); _Pragma("unroll") for (int m = 0; m < 4; ++m) _Pragma("unroll") for (int n = 0; n < 2; ++n) _Pragma("unroll") for (int k = 0; k < 2; ++k) \
;         acc[ai][bj][m][n] = pg8_mma<F16>(Bt[n][k], At[m][k], acc[ai][bj][m][n]); __builtin_amdgcn_s_setprio(0); } while (0)
; #define PG8_WAIT_V(n) asm volatile("s_waitcnt vmcnt(" #n ")" ::: "memory")
; #define PG8_WAIT_L(n) asm volatile("s_waitcnt lgkmcnt(" #n ")" ::: "memory")
; #define PG8_BAR __builtin_amdgcn_s_barrier()
; #define PG8_SCHED __builtin_amdgcn_sched_barrier(0)
; template <class Epi, class Sched, bool ALIGN_EPI = false, bool SP2 = false, bool F16 = false>
; __device__ __forceinline__ void gemm_phase(PG8_LAS unsigned char* lds, const Gemm g, const Sched& S, const Epi& E) {
;     ...
;             PG8_WAIT_V(8); PG8_WAIT_L(0); PG8_BAR; PG8_MMA(1, 0, At, B0); PG8_MMA(1, 1, At, B1); PG8_BAR; PG8_SCHED;
;             PG8_LDB(B0, 1, 0); PG8_LDB(B1, 1, 1); PG8_SCHED; PG8_LDA(At, 1, 0); PG8_STAGE(PG8_SA(0, 1), a2 + hstep, voffA);
;             PG8_WAIT_V(8); PG8_WAIT_L(0); PG8_BAR; PG8_MMA(0, 0, At, B0); PG8_MMA(0, 1, At, B1); PG8_BAR; PG8_SCHED;
.Lur_up_d1:
	s_waitcnt lgkmcnt(0)
	s_barrier
	s_setprio 1
	s_waitcnt lgkmcnt(0)
	v_mfma_f32_16x16x32_bf16 v[62:65], v[146:149], v[178:181], v[62:65]
	v_mfma_f32_16x16x32_bf16 v[58:61], v[154:157], v[178:181], v[58:61]
	v_mfma_f32_16x16x32_bf16 v[46:49], v[146:149], v[186:189], v[46:49]
	v_mfma_f32_16x16x32_bf16 v[42:45], v[154:157], v[186:189], v[42:45]
	v_mfma_f32_16x16x32_bf16 v[30:33], v[146:149], v[194:197], v[30:33]
	v_mfma_f32_16x16x32_bf16 v[26:29], v[154:157], v[194:197], v[26:29]
	v_mfma_f32_16x16x32_bf16 v[14:17], v[146:149], v[202:205], v[14:17]
	v_mfma_f32_16x16x32_bf16 v[10:13], v[154:157], v[202:205], v[10:13]
	v_mfma_f32_16x16x32_bf16 v[62:65], v[150:153], v[182:185], v[62:65]
	v_mfma_f32_16x16x32_bf16 v[58:61], v[158:161], v[182:185], v[58:61]
	v_mfma_f32_16x16x32_bf16 v[46:49], v[150:153], v[190:193], v[46:49]
	v_mfma_f32_16x16x32_bf16 v[42:45], v[158:161], v[190:193], v[42:45]
	v_mfma_f32_16x16x32_bf16 v[30:33], v[150:153], v[198:201], v[30:33]
	v_mfma_f32_16x16x32_bf16 v[26:29], v[158:161], v[198:201], v[26:29]
	v_mfma_f32_16x16x32_bf16 v[14:17], v[150:153], v[206:209], v[14:17]
	v_mfma_f32_16x16x32_bf16 v[10:13], v[158:161], v[206:209], v[10:13]
	s_setprio 0
	s_setprio 1
	v_mfma_f32_16x16x32_bf16 v[54:57], v[162:165], v[178:181], v[54:57]
	v_mfma_f32_16x16x32_bf16 v[50:53], v[170:173], v[178:181], v[50:53]
	v_mfma_f32_16x16x32_bf16 v[38:41], v[162:165], v[186:189], v[38:41]
	v_mfma_f32_16x16x32_bf16 v[34:37], v[170:173], v[186:189], v[34:37]
	v_mfma_f32_16x16x32_bf16 v[22:25], v[162:165], v[194:197], v[22:25]
	v_mfma_f32_16x16x32_bf16 v[18:21], v[170:173], v[194:197], v[18:21]
	v_mfma_f32_16x16x32_bf16 v[6:9], v[162:165], v[202:205], v[6:9]
	v_mfma_f32_16x16x32_bf16 v[2:5], v[170:173], v[202:205], v[2:5]
	v_mfma_f32_16x16x32_bf16 v[54:57], v[166:169], v[182:185], v[54:57]
	v_mfma_f32_16x16x32_bf16 v[50:53], v[174:177], v[182:185], v[50:53]
	v_mfma_f32_16x16x32_bf16 v[38:41], v[166:169], v[190:193], v[38:41]
	v_mfma_f32_16x16x32_bf16 v[34:37], v[174:177], v[190:193], v[34:37]
	v_mfma_f32_16x16x32_bf16 v[22:25], v[166:169], v[198:201], v[22:25]
	v_mfma_f32_16x16x32_bf16 v[18:21], v[174:177], v[198:201], v[18:21]
	v_mfma_f32_16x16x32_bf16 v[6:9], v[166:169], v[206:209], v[6:9]
	v_mfma_f32_16x16x32_bf16 v[2:5], v[174:177], v[206:209], v[2:5]
	s_setprio 0
	s_barrier
	s_add_i32 s69, 0, 0x18000
	s_add_i32 s70, 0, 0x1c000
	v_add_u32_e32 v158, s69, v143
	v_add_u32_e32 v174, s70, v143
	ds_read_b128 v[146:149], v158
	ds_read_b128 v[150:153], v158 offset:1024
	ds_read_b128 v[154:157], v158 offset:2048
	ds_read_b128 v[158:161], v158 offset:3072
	ds_read_b128 v[162:165], v174
	ds_read_b128 v[166:169], v174 offset:1024
	ds_read_b128 v[170:173], v174 offset:2048
	ds_read_b128 v[174:177], v174 offset:3072
	s_add_u32 s44, s44, 0x80000
	s_addc_u32 s45, s45, 0
	s_mov_b32 m0, s56
	v_lshl_add_u64 v[220:221], s[44:45], 0, v[134:135]
	ds_read_b128 v[178:181], v145 offset:32768
	ds_read_b128 v[182:185], v145 offset:33792
	ds_read_b128 v[186:189], v145 offset:34816
	ds_read_b128 v[190:193], v145 offset:35840
	ds_read_b128 v[194:197], v145 offset:36864
	ds_read_b128 v[198:201], v145 offset:37888
	ds_read_b128 v[202:205], v145 offset:38912
	ds_read_b128 v[206:209], v145 offset:39936
	global_load_lds_dwordx4 v[220:221], off
	v_lshl_add_u64 v[220:221], s[44:45], 0, v[132:133]
	s_mov_b32 m0, s57
	s_nop 0
	global_load_lds_dwordx4 v[220:221], off
	s_waitcnt vmcnt(8)
	s_waitcnt lgkmcnt(0)
	s_barrier
	s_setprio 1
	s_waitcnt lgkmcnt(0)
	v_mfma_f32_16x16x32_bf16 v[126:129], v[146:149], v[178:181], v[126:129]
	v_mfma_f32_16x16x32_bf16 v[122:125], v[154:157], v[178:181], v[122:125]
	v_mfma_f32_16x16x32_bf16 v[110:113], v[146:149], v[186:189], v[110:113]
	v_mfma_f32_16x16x32_bf16 v[106:109], v[154:157], v[186:189], v[106:109]
	v_mfma_f32_16x16x32_bf16 v[94:97], v[146:149], v[194:197], v[94:97]
	v_mfma_f32_16x16x32_bf16 v[90:93], v[154:157], v[194:197], v[90:93]
	v_mfma_f32_16x16x32_bf16 v[78:81], v[146:149], v[202:205], v[78:81]
	v_mfma_f32_16x16x32_bf16 v[74:77], v[154:157], v[202:205], v[74:77]
	v_mfma_f32_16x16x32_bf16 v[126:129], v[150:153], v[182:185], v[126:129]
	v_mfma_f32_16x16x32_bf16 v[122:125], v[158:161], v[182:185], v[122:125]
	v_mfma_f32_16x16x32_bf16 v[110:113], v[150:153], v[190:193], v[110:113]
	v_mfma_f32_16x16x32_bf16 v[106:109], v[158:161], v[190:193], v[106:109]
	v_mfma_f32_16x16x32_bf16 v[94:97], v[150:153], v[198:201], v[94:97]
	v_mfma_f32_16x16x32_bf16 v[90:93], v[158:161], v[198:201], v[90:93]
	v_mfma_f32_16x16x32_bf16 v[78:81], v[150:153], v[206:209], v[78:81]
	v_mfma_f32_16x16x32_bf16 v[74:77], v[158:161], v[206:209], v[74:77]
	s_setprio 0
	s_setprio 1
	v_mfma_f32_16x16x32_bf16 v[118:121], v[162:165], v[178:181], v[118:121]
	v_mfma_f32_16x16x32_bf16 v[114:117], v[170:173], v[178:181], v[114:117]
	v_mfma_f32_16x16x32_bf16 v[102:105], v[162:165], v[186:189], v[102:105]
	v_mfma_f32_16x16x32_bf16 v[98:101], v[170:173], v[186:189], v[98:101]
	v_mfma_f32_16x16x32_bf16 v[86:89], v[162:165], v[194:197], v[86:89]
	v_mfma_f32_16x16x32_bf16 v[82:85], v[170:173], v[194:197], v[82:85]
	v_mfma_f32_16x16x32_bf16 v[70:73], v[162:165], v[202:205], v[70:73]
	v_mfma_f32_16x16x32_bf16 v[66:69], v[170:173], v[202:205], v[66:69]
	v_mfma_f32_16x16x32_bf16 v[118:121], v[166:169], v[182:185], v[118:121]
	v_mfma_f32_16x16x32_bf16 v[114:117], v[174:177], v[182:185], v[114:117]
	v_mfma_f32_16x16x32_bf16 v[102:105], v[166:169], v[190:193], v[102:105]
	v_mfma_f32_16x16x32_bf16 v[98:101], v[174:177], v[190:193], v[98:101]
	v_mfma_f32_16x16x32_bf16 v[86:89], v[166:169], v[198:201], v[86:89]
	v_mfma_f32_16x16x32_bf16 v[82:85], v[174:177], v[198:201], v[82:85]
	v_mfma_f32_16x16x32_bf16 v[70:73], v[166:169], v[206:209], v[70:73]
	v_mfma_f32_16x16x32_bf16 v[66:69], v[174:177], v[206:209], v[66:69]
	s_setprio 0
	s_barrier
; #define PG8_STAGE(bufoff, gbase, voff) do { _Pragma("unroll") for (int _i = 0; _i < 2; ++_i) \
;         __builtin_amdgcn_global_load_lds((const unsigned*)((const char*)(gbase) + (voff)[_i]), (PG8_LAS unsigned*)(lds + (bufoff) + ldsw + _i * 8192), 16, 0, 0); } while (0)
; #define PG8_LDA(dst, b, h) do { _Pragma("unroll") for (int m = 0; m < 4; ++m) _Pragma("unroll") for (int k = 0; k < 2; ++k) dst[m][k] = *(const PG8_LAS bf16x8*)(lds + PG8_SA(b, h) + aoff + m * 2048 + k * 1024); } while (0)
; #define PG8_MMA(ai, bj, At, Bt) do { __builtin_amdgcn_s_setprio(1); _Pragma("unroll") for (int m = 0; m < 4; ++m) _Pragma("unroll") for (int n = 0; n < 2; ++n) _Pragma("unroll") for (int k = 0; k < 2; ++k) \
;         acc[ai][bj][m][n] = pg8_mma<F16>(Bt[n][k], At[m][k], acc[ai][bj][m][n]); __builtin_amdgcn_s_setprio(0); } while (0)
; #define PG8_WAIT_V(n) asm volatile("s_waitcnt vmcnt(" #n ")" ::: "memory")
; #define PG8_WAIT_L(n) asm volatile("s_waitcnt lgkmcnt(" #n ")" ::: "memory")
; #define PG8_BAR __builtin_amdgcn_s_barrier()
; #define PG8_SCHED __builtin_amdgcn_sched_barrier(0)
; template <class Epi, class Sched, bool ALIGN_EPI = false, bool SP2 = false, bool F16 = false>
; __device__ __forceinline__ void gemm_phase(PG8_LAS unsigned char* lds, const Gemm g, const Sched& S, const Epi& E) {
;     ...
;         for (int t = 0; t < nt; t += 2) {
;             const bool last = (t == nt - 2);
;             const char* a1 = cA + (size_t)(t + 1) * kstep;
;             const char* a2 = last ? nA : cA + (size_t)(t + 2) * kstep; const char* b2 = last ? nB : cB + (size_t)(t + 2) * kstep;
;             const char* a3 = a2 + kstep; const char* b3 = b2 + kstep;
;     ...
;             PG8_LDA(At, 1, 1); PG8_STAGE(PG8_SB(1, 0), b3, voffB); PG8_STAGE(PG8_SB(1, 1), b3 + hstep, voffB); PG8_STAGE(PG8_SA(1, 0), a3, voffA);
;             PG8_WAIT_V(8); PG8_WAIT_L(0); PG8_BAR; PG8_MMA(1, 0, At, B0); PG8_MMA(1, 1, At, B1); PG8_BAR; PG8_SCHED;
	s_add_i32 s44, s69, s53
	v_lshl_add_u64 v[140:141], v[140:141], 0, s[24:25]
	s_mov_b32 m0, s44
	ds_read_b128 v[178:181], v145 offset:49152
	ds_read_b128 v[182:185], v145 offset:50176
	ds_read_b128 v[186:189], v145 offset:51200
	ds_read_b128 v[190:193], v145 offset:52224
	ds_read_b128 v[194:197], v145 offset:53248
	ds_read_b128 v[198:201], v145 offset:54272
	ds_read_b128 v[202:205], v145 offset:55296
	ds_read_b128 v[206:209], v145 offset:56320
	global_load_lds_dwordx4 v[140:141], off
	s_add_i32 m0, s44, 0x2000
	s_add_u32 s42, s42, 0x80080
	v_lshl_add_u64 v[140:141], v[210:211], 0, s[24:25]
	s_addc_u32 s43, s43, 0
	s_add_i32 s44, s70, s53
	global_load_lds_dwordx4 v[140:141], off
	v_lshl_add_u64 v[140:141], s[42:43], 0, v[0:1]
	s_mov_b32 m0, s44
	s_nop 0
	global_load_lds_dwordx4 v[140:141], off
	v_lshl_add_u64 v[140:141], s[42:43], 0, v[130:131]
	s_add_i32 m0, s44, 0x2000
	s_nop 0
	global_load_lds_dwordx4 v[140:141], off
	v_lshl_add_u64 v[140:141], v[212:213], 0, s[24:25]
	s_mov_b32 m0, s58
	s_nop 0
	global_load_lds_dwordx4 v[140:141], off
	v_lshl_add_u64 v[140:141], v[214:215], 0, s[24:25]
	s_mov_b32 m0, s59
	s_nop 0
	global_load_lds_dwordx4 v[140:141], off
	s_waitcnt vmcnt(8)
	s_waitcnt lgkmcnt(0)
	s_barrier
	s_setprio 1
	s_waitcnt lgkmcnt(0)
	v_mfma_f32_16x16x32_bf16 v[62:65], v[146:149], v[178:181], v[62:65]
	v_mfma_f32_16x16x32_bf16 v[58:61], v[154:157], v[178:181], v[58:61]
	v_mfma_f32_16x16x32_bf16 v[46:49], v[146:149], v[186:189], v[46:49]
	v_mfma_f32_16x16x32_bf16 v[42:45], v[154:157], v[186:189], v[42:45]
	v_mfma_f32_16x16x32_bf16 v[30:33], v[146:149], v[194:197], v[30:33]
	v_mfma_f32_16x16x32_bf16 v[26:29], v[154:157], v[194:197], v[26:29]
	v_mfma_f32_16x16x32_bf16 v[14:17], v[146:149], v[202:205], v[14:17]
	v_mfma_f32_16x16x32_bf16 v[10:13], v[154:157], v[202:205], v[10:13]
	v_mfma_f32_16x16x32_bf16 v[62:65], v[150:153], v[182:185], v[62:65]
	v_mfma_f32_16x16x32_bf16 v[58:61], v[158:161], v[182:185], v[58:61]
	v_mfma_f32_16x16x32_bf16 v[46:49], v[150:153], v[190:193], v[46:49]
	v_mfma_f32_16x16x32_bf16 v[42:45], v[158:161], v[190:193], v[42:45]
	v_mfma_f32_16x16x32_bf16 v[30:33], v[150:153], v[198:201], v[30:33]
	v_mfma_f32_16x16x32_bf16 v[26:29], v[158:161], v[198:201], v[26:29]
	v_mfma_f32_16x16x32_bf16 v[14:17], v[150:153], v[206:209], v[14:17]
	v_mfma_f32_16x16x32_bf16 v[10:13], v[158:161], v[206:209], v[10:13]
	s_setprio 0
	s_setprio 1
	v_mfma_f32_16x16x32_bf16 v[54:57], v[162:165], v[178:181], v[54:57]
	v_mfma_f32_16x16x32_bf16 v[50:53], v[170:173], v[178:181], v[50:53]
	v_mfma_f32_16x16x32_bf16 v[38:41], v[162:165], v[186:189], v[38:41]
	v_mfma_f32_16x16x32_bf16 v[34:37], v[170:173], v[186:189], v[34:37]
	v_mfma_f32_16x16x32_bf16 v[22:25], v[162:165], v[194:197], v[22:25]
	v_mfma_f32_16x16x32_bf16 v[18:21], v[170:173], v[194:197], v[18:21]
	v_mfma_f32_16x16x32_bf16 v[6:9], v[162:165], v[202:205], v[6:9]
	v_mfma_f32_16x16x32_bf16 v[2:5], v[170:173], v[202:205], v[2:5]
	s_add_i32 s68, s68, 2
	s_add_u32 s26, s26, 0x100
	s_addc_u32 s27, s27, 0
	s_add_u32 s66, s66, 0x100
	s_addc_u32 s67, s67, 0
	s_add_u32 s42, s26, 0xfff80080
	s_addc_u32 s43, s27, -1
	s_add_i32 s69, 0, 0x10000
	s_cmp_eq_u32 s68, 28
	s_cselect_b32 s45, s17, s43
	s_cselect_b32 s44, s64, s42
	s_cselect_b32 s43, s15, s67
	s_cselect_b32 s42, s65, s66
	s_add_i32 s72, 0, 0x14000
	s_cmp_gt_u32 s68, 29
	v_mfma_f32_16x16x32_bf16 v[54:57], v[166:169], v[182:185], v[54:57]
	v_mfma_f32_16x16x32_bf16 v[50:53], v[174:177], v[182:185], v[50:53]
	v_mfma_f32_16x16x32_bf16 v[38:41], v[166:169], v[190:193], v[38:41]
	v_mfma_f32_16x16x32_bf16 v[34:37], v[174:177], v[190:193], v[34:37]
	v_mfma_f32_16x16x32_bf16 v[22:25], v[166:169], v[198:201], v[22:25]
	v_mfma_f32_16x16x32_bf16 v[18:21], v[174:177], v[198:201], v[18:21]
	v_mfma_f32_16x16x32_bf16 v[6:9], v[166:169], v[206:209], v[6:9]
	v_mfma_f32_16x16x32_bf16 v[2:5], v[174:177], v[206:209], v[2:5]
	s_setprio 0
	s_barrier
	s_cbranch_scc0 .LBB0_1816
	s_and_b64 vcc, exec, s[12:13]
	s_cbranch_vccz .LBB0_1819
	s_barrier

; #define PG8_STAGE(bufoff, gbase, voff) do { _Pragma("unroll") for (int _i = 0; _i < 2; ++_i) \
;         __builtin_amdgcn_global_load_lds((const unsigned*)((const char*)(gbase) + (voff)[_i]), (PG8_LAS unsigned*)(lds + (bufoff) + ldsw + _i * 8192), 16, 0, 0); } while (0)
; #define PG8_LDA(dst, b, h) do { _Pragma("unroll") for (int m = 0; m < 4; ++m) _Pragma("unroll") for (int k = 0; k < 2; ++k) dst[m][k] = *(const PG8_LAS bf16x8*)(lds + PG8_SA(b, h) + aoff + m * 2048 + k * 1024); } while (0)
; #define PG8_LDB(dst, b, h) do { _Pragma("unroll") for (int n = 0; n < 2; ++n) _Pragma("unroll") for (int k = 0; k < 2; ++k) dst[n][k] = *(const PG8_LAS bf16x8*)(lds + PG8_SB(b, h) + boff + n * 2048 + k * 1024); } while (0)
; #define PG8_MMA(ai, bj, At, Bt) do { __builtin_amdgcn_s_setprio(1); _Pragma("unroll") for (int m = 0; m < 4; ++m) _Pragma("unroll") for (int n = 0; n < 2; ++n) _Pragma("unroll") for (int k = 0; k < 2; ++k) \
;         acc[ai][bj][m][n] = pg8_mma<F16>(Bt[n][k], At[m][k], acc[ai][bj][m][n]); __builtin_amdgcn_s_setprio(0); } while (0)
; #define PG8_WAIT_V(n) asm volatile("s_waitcnt vmcnt(" #n ")" ::: "memory")
; #define PG8_WAIT_L(n) asm volatile("s_waitcnt lgkmcnt(" #n ")" ::: "memory")
; #define PG8_BAR __builtin_amdgcn_s_barrier()
; template <class Epi, class Sched, bool ALIGN_EPI = false, bool SP2 = false, bool F16 = false>
; __device__ __forceinline__ void gemm_phase(PG8_LAS unsigned char* lds, const Gemm g, const Sched& S, const Epi& E) {
;     ...
;         const bool has_next = S.next(ui + 1, nxt);
;         const char* nA = has_next ? (const char*)g.A + (size_t)nxt.pm * tstep : cA; const char* nB = has_next ? (const char*)g.Bt + (size_t)nxt.pn * tstep : cB;
;         for (int t = 0; t < nt; t += 2) {
;             const bool last = (t == nt - 2);
;             const char* a1 = cA + (size_t)(t + 1) * kstep;
;             const char* a2 = last ? nA : cA + (size_t)(t + 2) * kstep; const char* b2 = last ? nB : cB + (size_t)(t + 2) * kstep;
;             const char* a3 = a2 + kstep; const char* b3 = b2 + kstep;
;             if (last && has_next) S.a_ready(nxt);
;             if constexpr (SP2) {
;             PG8_LDB(B0, 0, 0); PG8_LDB(B1, 0, 1); PG8_SCHED; PG8_LDA(At, 0, 0); PG8_STAGE(PG8_SA(1, 1), a1 + hstep, voffA);
;             PG8_WAIT_V(8); PG8_WAIT_L(0); PG8_BAR; PG8_MMA(0, 0, At, B0); PG8_MMA(0, 1, At, B1); PG8_BAR; PG8_SCHED;
.LBB0_2497:
	s_add_u32 s42, s12, 0x100
	s_addc_u32 s43, s13, 0
	s_add_u32 s12, s0, 0x160080
	s_addc_u32 s13, s1, 0
	v_lshl_add_u64 v[140:141], s[12:13], 0, v[136:137]
	v_lshl_add_u64 v[142:143], s[12:13], 0, v[138:139]
	s_mov_b32 s67, -2
	s_mov_b64 s[12:13], 0
	s_add_u32 s14, s0, s12
	s_addc_u32 s15, s1, s13
	s_add_u32 s14, s14, 0x100
	s_addc_u32 s15, s15, 0
	s_add_u32 s68, s42, s12
	s_addc_u32 s69, s43, s13
	s_add_i32 s70, 0, 0x10000
	s_cmpk_eq_i32 s12, 0x2b00
	s_cselect_b32 s17, s11, s15
	s_cselect_b32 s16, s10, s14
	s_cselect_b32 s15, s9, s69
	s_cselect_b32 s14, s8, s68
	s_add_i32 s71, 0, 0x14000
.LBB0_2498:
	v_add_u32_e32 v158, s70, v144
	v_add_u32_e32 v174, s71, v144
	ds_read_b128 v[146:149], v158
	ds_read_b128 v[150:153], v158 offset:1024
	ds_read_b128 v[154:157], v158 offset:2048
	ds_read_b128 v[158:161], v158 offset:3072
	ds_read_b128 v[162:165], v174
	ds_read_b128 v[166:169], v174 offset:1024
	ds_read_b128 v[170:173], v174 offset:2048
	ds_read_b128 v[174:177], v174 offset:3072
	v_lshl_add_u64 v[210:211], v[140:141], 0, s[12:13]
	s_add_i32 m0, s57, 0xc000
	ds_read_b128 v[178:181], v145
	ds_read_b128 v[182:185], v145 offset:1024
	ds_read_b128 v[186:189], v145 offset:2048
	ds_read_b128 v[190:193], v145 offset:3072
	ds_read_b128 v[194:197], v145 offset:4096
	ds_read_b128 v[198:201], v145 offset:5120
	ds_read_b128 v[202:205], v145 offset:6144
	ds_read_b128 v[206:209], v145 offset:7168
	global_load_lds_dwordx4 v[210:211], off
	v_lshl_add_u64 v[210:211], v[142:143], 0, s[12:13]
	s_add_i32 m0, s57, 0xe000
	s_nop 0
	global_load_lds_dwordx4 v[210:211], off
	s_waitcnt vmcnt(8)
	s_waitcnt lgkmcnt(0)
	s_barrier
	s_setprio 1
	s_waitcnt lgkmcnt(0)
	v_mfma_f32_16x16x32_bf16 v[126:129], v[146:149], v[178:181], v[126:129]
	v_mfma_f32_16x16x32_bf16 v[122:125], v[154:157], v[178:181], v[122:125]
	v_mfma_f32_16x16x32_bf16 v[110:113], v[146:149], v[186:189], v[110:113]
	v_mfma_f32_16x16x32_bf16 v[106:109], v[154:157], v[186:189], v[106:109]
	v_mfma_f32_16x16x32_bf16 v[94:97], v[146:149], v[194:197], v[94:97]
	v_mfma_f32_16x16x32_bf16 v[90:93], v[154:157], v[194:197], v[90:93]
	v_mfma_f32_16x16x32_bf16 v[78:81], v[146:149], v[202:205], v[78:81]
	v_mfma_f32_16x16x32_bf16 v[74:77], v[154:157], v[202:205], v[74:77]
	v_mfma_f32_16x16x32_bf16 v[126:129], v[150:153], v[182:185], v[126:129]
	v_mfma_f32_16x16x32_bf16 v[122:125], v[158:161], v[182:185], v[122:125]
	v_mfma_f32_16x16x32_bf16 v[110:113], v[150:153], v[190:193], v[110:113]
	v_mfma_f32_16x16x32_bf16 v[106:109], v[158:161], v[190:193], v[106:109]
	v_mfma_f32_16x16x32_bf16 v[94:97], v[150:153], v[198:201], v[94:97]
	v_mfma_f32_16x16x32_bf16 v[90:93], v[158:161], v[198:201], v[90:93]
	v_mfma_f32_16x16x32_bf16 v[78:81], v[150:153], v[206:209], v[78:81]
	v_mfma_f32_16x16x32_bf16 v[74:77], v[158:161], v[206:209], v[74:77]
	s_setprio 0
	s_setprio 1
	v_mfma_f32_16x16x32_bf16 v[118:121], v[162:165], v[178:181], v[118:121]
	v_mfma_f32_16x16x32_bf16 v[114:117], v[170:173], v[178:181], v[114:117]
	v_mfma_f32_16x16x32_bf16 v[102:105], v[162:165], v[186:189], v[102:105]
	v_mfma_f32_16x16x32_bf16 v[98:101], v[170:173], v[186:189], v[98:101]
	v_mfma_f32_16x16x32_bf16 v[86:89], v[162:165], v[194:197], v[86:89]
	v_mfma_f32_16x16x32_bf16 v[82:85], v[170:173], v[194:197], v[82:85]
	v_mfma_f32_16x16x32_bf16 v[70:73], v[162:165], v[202:205], v[70:73]
	v_mfma_f32_16x16x32_bf16 v[66:69], v[170:173], v[202:205], v[66:69]
	v_mfma_f32_16x16x32_bf16 v[118:121], v[166:169], v[182:185], v[118:121]
	v_mfma_f32_16x16x32_bf16 v[114:117], v[174:177], v[182:185], v[114:117]
	v_mfma_f32_16x16x32_bf16 v[102:105], v[166:169], v[190:193], v[102:105]
	v_mfma_f32_16x16x32_bf16 v[98:101], v[174:177], v[190:193], v[98:101]
	v_mfma_f32_16x16x32_bf16 v[86:89], v[166:169], v[198:201], v[86:89]
	v_mfma_f32_16x16x32_bf16 v[82:85], v[174:177], v[198:201], v[82:85]
	v_mfma_f32_16x16x32_bf16 v[70:73], v[166:169], v[206:209], v[70:73]
	v_mfma_f32_16x16x32_bf16 v[66:69], v[174:177], v[206:209], v[66:69]
	s_setprio 0
	s_barrier
	s_add_i32 s68, s70, s56
	v_lshl_add_u64 v[210:211], s[14:15], 0, v[0:1]
	s_mov_b32 m0, s68
	ds_read_b128 v[178:181], v145 offset:16384
	ds_read_b128 v[182:185], v145 offset:17408
	ds_read_b128 v[186:189], v145 offset:18432
	ds_read_b128 v[190:193], v145 offset:19456
	ds_read_b128 v[194:197], v145 offset:20480
	ds_read_b128 v[198:201], v145 offset:21504
	ds_read_b128 v[202:205], v145 offset:22528
	ds_read_b128 v[206:209], v145 offset:23552
	global_load_lds_dwordx4 v[210:211], off
	s_add_i32 m0, s68, 0x2000
	s_add_u32 s68, s14, 0x160000
	v_lshl_add_u64 v[212:213], s[14:15], 0, v[130:131]
	s_addc_u32 s69, s15, 0
	s_add_i32 s70, s71, s56
	global_load_lds_dwordx4 v[212:213], off
	v_lshl_add_u64 v[220:221], s[68:69], 0, v[0:1]
	s_mov_b32 m0, s70
	v_lshl_add_u64 v[222:223], s[16:17], 0, v[132:133]
	global_load_lds_dwordx4 v[220:221], off
	v_lshl_add_u64 v[220:221], s[68:69], 0, v[130:131]
	s_add_i32 m0, s70, 0x2000
	s_nop 0
	global_load_lds_dwordx4 v[220:221], off
	v_lshl_add_u64 v[220:221], s[16:17], 0, v[134:135]
	s_mov_b32 m0, s57
	s_nop 0
	global_load_lds_dwordx4 v[220:221], off
	s_mov_b32 m0, s58
	s_nop 0
	global_load_lds_dwordx4 v[222:223], off
	s_waitcnt vmcnt(8)
	s_waitcnt lgkmcnt(0)
	s_barrier
; #define PG8_STAGE(bufoff, gbase, voff) do { _Pragma("unroll") for (int _i = 0; _i < 2; ++_i) \
;         __builtin_amdgcn_global_load_lds((const unsigned*)((const char*)(gbase) + (voff)[_i]), (PG8_LAS unsigned*)(lds + (bufoff) + ldsw + _i * 8192), 16, 0, 0); } while (0)
; #define PG8_LDA(dst, b, h) do { _Pragma("unroll") for (int m = 0; m < 4; ++m) _Pragma("unroll") for (int k = 0; k < 2; ++k) dst[m][k] = *(const PG8_LAS bf16x8*)(lds + PG8_SA(b, h) + aoff + m * 2048 + k * 1024); } while (0)
; #define PG8_LDB(dst, b, h) do { _Pragma("unroll") for (int n = 0; n < 2; ++n) _Pragma("unroll") for (int k = 0; k < 2; ++k) dst[n][k] = *(const PG8_LAS bf16x8*)(lds + PG8_SB(b, h) + boff + n * 2048 + k * 1024); } while (0)
; #define PG8_MMA(ai, bj, At, Bt) do { __builtin_amdgcn_s_setprio(1); _Pragma("unroll") for (int m = 0; m < 4; ++m) _Pragma("unroll") for (int n = 0; n < 2; ++n) _Pragma("unroll") for (int k = 0; k < 2; ++k) \
;         acc[ai][bj][m][n] = pg8_mma<F16>(Bt[n][k], At[m][k], acc[ai][bj][m][n]); __builtin_amdgcn_s_setprio(0); } while (0)
; #define PG8_WAIT_V(n) asm volatile("s_waitcnt vmcnt(" #n ")" ::: "memory")
; #define PG8_WAIT_L(n) asm volatile("s_waitcnt lgkmcnt(" #n ")" ::: "memory")
; #define PG8_BAR __builtin_amdgcn_s_barrier()
; #define PG8_SCHED __builtin_amdgcn_sched_barrier(0)
; template <class Epi, class Sched, bool ALIGN_EPI = false, bool SP2 = false, bool F16 = false>
; __device__ __forceinline__ void gemm_phase(PG8_LAS unsigned char* lds, const Gemm g, const Sched& S, const Epi& E) {
;     ...
;             PG8_WAIT_V(8); PG8_WAIT_L(0); PG8_BAR; PG8_MMA(1, 0, At, B0); PG8_MMA(1, 1, At, B1); PG8_BAR; PG8_SCHED;
;             PG8_LDB(B0, 1, 0); PG8_LDB(B1, 1, 1); PG8_SCHED; PG8_LDA(At, 1, 0); PG8_STAGE(PG8_SA(0, 1), a2 + hstep, voffA);
;             PG8_WAIT_V(8); PG8_WAIT_L(0); PG8_BAR; PG8_MMA(0, 0, At, B0); PG8_MMA(0, 1, At, B1); PG8_BAR; PG8_SCHED;
	s_setprio 1
	s_waitcnt lgkmcnt(0)
	v_mfma_f32_16x16x32_bf16 v[62:65], v[146:149], v[178:181], v[62:65]
	v_mfma_f32_16x16x32_bf16 v[58:61], v[154:157], v[178:181], v[58:61]
	v_mfma_f32_16x16x32_bf16 v[46:49], v[146:149], v[186:189], v[46:49]
	v_mfma_f32_16x16x32_bf16 v[42:45], v[154:157], v[186:189], v[42:45]
	v_mfma_f32_16x16x32_bf16 v[30:33], v[146:149], v[194:197], v[30:33]
	v_mfma_f32_16x16x32_bf16 v[26:29], v[154:157], v[194:197], v[26:29]
	v_mfma_f32_16x16x32_bf16 v[14:17], v[146:149], v[202:205], v[14:17]
	v_mfma_f32_16x16x32_bf16 v[10:13], v[154:157], v[202:205], v[10:13]
	v_mfma_f32_16x16x32_bf16 v[62:65], v[150:153], v[182:185], v[62:65]
	v_mfma_f32_16x16x32_bf16 v[58:61], v[158:161], v[182:185], v[58:61]
	v_mfma_f32_16x16x32_bf16 v[46:49], v[150:153], v[190:193], v[46:49]
	v_mfma_f32_16x16x32_bf16 v[42:45], v[158:161], v[190:193], v[42:45]
	v_mfma_f32_16x16x32_bf16 v[30:33], v[150:153], v[198:201], v[30:33]
	v_mfma_f32_16x16x32_bf16 v[26:29], v[158:161], v[198:201], v[26:29]
	v_mfma_f32_16x16x32_bf16 v[14:17], v[150:153], v[206:209], v[14:17]
	v_mfma_f32_16x16x32_bf16 v[10:13], v[158:161], v[206:209], v[10:13]
	s_setprio 0
	s_setprio 1
	v_mfma_f32_16x16x32_bf16 v[54:57], v[162:165], v[178:181], v[54:57]
	v_mfma_f32_16x16x32_bf16 v[50:53], v[170:173], v[178:181], v[50:53]
	v_mfma_f32_16x16x32_bf16 v[38:41], v[162:165], v[186:189], v[38:41]
	v_mfma_f32_16x16x32_bf16 v[34:37], v[170:173], v[186:189], v[34:37]
	v_mfma_f32_16x16x32_bf16 v[22:25], v[162:165], v[194:197], v[22:25]
	v_mfma_f32_16x16x32_bf16 v[18:21], v[170:173], v[194:197], v[18:21]
	v_mfma_f32_16x16x32_bf16 v[6:9], v[162:165], v[202:205], v[6:9]
	v_mfma_f32_16x16x32_bf16 v[2:5], v[170:173], v[202:205], v[2:5]
	v_mfma_f32_16x16x32_bf16 v[54:57], v[166:169], v[182:185], v[54:57]
	v_mfma_f32_16x16x32_bf16 v[50:53], v[174:177], v[182:185], v[50:53]
	v_mfma_f32_16x16x32_bf16 v[38:41], v[166:169], v[190:193], v[38:41]
	v_mfma_f32_16x16x32_bf16 v[34:37], v[174:177], v[190:193], v[34:37]
	v_mfma_f32_16x16x32_bf16 v[22:25], v[166:169], v[198:201], v[22:25]
	v_mfma_f32_16x16x32_bf16 v[18:21], v[174:177], v[198:201], v[18:21]
	v_mfma_f32_16x16x32_bf16 v[6:9], v[166:169], v[206:209], v[6:9]
	v_mfma_f32_16x16x32_bf16 v[2:5], v[174:177], v[206:209], v[2:5]
	s_setprio 0
	s_barrier
	s_add_i32 s68, 0, 0x18000
	s_add_i32 s69, 0, 0x1c000
	v_add_u32_e32 v158, s68, v144
	v_add_u32_e32 v174, s69, v144
	ds_read_b128 v[146:149], v158
	ds_read_b128 v[150:153], v158 offset:1024
	ds_read_b128 v[154:157], v158 offset:2048
	ds_read_b128 v[158:161], v158 offset:3072
	ds_read_b128 v[162:165], v174
	ds_read_b128 v[166:169], v174 offset:1024
	ds_read_b128 v[170:173], v174 offset:2048
	ds_read_b128 v[174:177], v174 offset:3072
	s_add_u32 s16, s16, 0x160000
	s_addc_u32 s17, s17, 0
	s_mov_b32 m0, s59
	v_lshl_add_u64 v[224:225], s[16:17], 0, v[134:135]
	ds_read_b128 v[178:181], v145 offset:32768
	ds_read_b128 v[182:185], v145 offset:33792
	ds_read_b128 v[186:189], v145 offset:34816
	ds_read_b128 v[190:193], v145 offset:35840
	ds_read_b128 v[194:197], v145 offset:36864
	ds_read_b128 v[198:201], v145 offset:37888
	ds_read_b128 v[202:205], v145 offset:38912
	ds_read_b128 v[206:209], v145 offset:39936
	global_load_lds_dwordx4 v[224:225], off
	v_lshl_add_u64 v[224:225], s[16:17], 0, v[132:133]
	s_mov_b32 m0, s60
	s_nop 0
	global_load_lds_dwordx4 v[224:225], off
	s_waitcnt vmcnt(8)
	s_waitcnt lgkmcnt(0)
	s_barrier
	s_setprio 1
	s_waitcnt lgkmcnt(0)
	v_mfma_f32_16x16x32_bf16 v[126:129], v[146:149], v[178:181], v[126:129]
	v_mfma_f32_16x16x32_bf16 v[122:125], v[154:157], v[178:181], v[122:125]
	v_mfma_f32_16x16x32_bf16 v[110:113], v[146:149], v[186:189], v[110:113]
	v_mfma_f32_16x16x32_bf16 v[106:109], v[154:157], v[186:189], v[106:109]
	v_mfma_f32_16x16x32_bf16 v[94:97], v[146:149], v[194:197], v[94:97]
	v_mfma_f32_16x16x32_bf16 v[90:93], v[154:157], v[194:197], v[90:93]
	v_mfma_f32_16x16x32_bf16 v[78:81], v[146:149], v[202:205], v[78:81]
	v_mfma_f32_16x16x32_bf16 v[74:77], v[154:157], v[202:205], v[74:77]
	v_mfma_f32_16x16x32_bf16 v[126:129], v[150:153], v[182:185], v[126:129]
	v_mfma_f32_16x16x32_bf16 v[122:125], v[158:161], v[182:185], v[122:125]
	v_mfma_f32_16x16x32_bf16 v[110:113], v[150:153], v[190:193], v[110:113]
	v_mfma_f32_16x16x32_bf16 v[106:109], v[158:161], v[190:193], v[106:109]
	v_mfma_f32_16x16x32_bf16 v[94:97], v[150:153], v[198:201], v[94:97]
	v_mfma_f32_16x16x32_bf16 v[90:93], v[158:161], v[198:201], v[90:93]
	v_mfma_f32_16x16x32_bf16 v[78:81], v[150:153], v[206:209], v[78:81]
	v_mfma_f32_16x16x32_bf16 v[74:77], v[158:161], v[206:209], v[74:77]
	s_setprio 0
	s_setprio 1
	v_mfma_f32_16x16x32_bf16 v[118:121], v[162:165], v[178:181], v[118:121]
	v_mfma_f32_16x16x32_bf16 v[114:117], v[170:173], v[178:181], v[114:117]
	v_mfma_f32_16x16x32_bf16 v[102:105], v[162:165], v[186:189], v[102:105]
	v_mfma_f32_16x16x32_bf16 v[98:101], v[170:173], v[186:189], v[98:101]
	v_mfma_f32_16x16x32_bf16 v[86:89], v[162:165], v[194:197], v[86:89]
	v_mfma_f32_16x16x32_bf16 v[82:85], v[170:173], v[194:197], v[82:85]
	v_mfma_f32_16x16x32_bf16 v[70:73], v[162:165], v[202:205], v[70:73]
	v_mfma_f32_16x16x32_bf16 v[66:69], v[170:173], v[202:205], v[66:69]
	v_mfma_f32_16x16x32_bf16 v[118:121], v[166:169], v[182:185], v[118:121]
	v_mfma_f32_16x16x32_bf16 v[114:117], v[174:177], v[182:185], v[114:117]
	v_mfma_f32_16x16x32_bf16 v[102:105], v[166:169], v[190:193], v[102:105]
	v_mfma_f32_16x16x32_bf16 v[98:101], v[174:177], v[190:193], v[98:101]
	v_mfma_f32_16x16x32_bf16 v[86:89], v[166:169], v[198:201], v[86:89]
	v_mfma_f32_16x16x32_bf16 v[82:85], v[174:177], v[198:201], v[82:85]
	v_mfma_f32_16x16x32_bf16 v[70:73], v[166:169], v[206:209], v[70:73]
	v_mfma_f32_16x16x32_bf16 v[66:69], v[174:177], v[206:209], v[66:69]
	s_setprio 0
	s_barrier
; #define PG8_STAGE(bufoff, gbase, voff) do { _Pragma("unroll") for (int _i = 0; _i < 2; ++_i) \
;         __builtin_amdgcn_global_load_lds((const unsigned*)((const char*)(gbase) + (voff)[_i]), (PG8_LAS unsigned*)(lds + (bufoff) + ldsw + _i * 8192), 16, 0, 0); } while (0)
; #define PG8_LDA(dst, b, h) do { _Pragma("unroll") for (int m = 0; m < 4; ++m) _Pragma("unroll") for (int k = 0; k < 2; ++k) dst[m][k] = *(const PG8_LAS bf16x8*)(lds + PG8_SA(b, h) + aoff + m * 2048 + k * 1024); } while (0)
; #define PG8_MMA(ai, bj, At, Bt) do { __builtin_amdgcn_s_setprio(1); _Pragma("unroll") for (int m = 0; m < 4; ++m) _Pragma("unroll") for (int n = 0; n < 2; ++n) _Pragma("unroll") for (int k = 0; k < 2; ++k) \
;         acc[ai][bj][m][n] = pg8_mma<F16>(Bt[n][k], At[m][k], acc[ai][bj][m][n]); __builtin_amdgcn_s_setprio(0); } while (0)
; #define PG8_WAIT_V(n) asm volatile("s_waitcnt vmcnt(" #n ")" ::: "memory")
; #define PG8_WAIT_L(n) asm volatile("s_waitcnt lgkmcnt(" #n ")" ::: "memory")
; #define PG8_BAR __builtin_amdgcn_s_barrier()
; #define PG8_SCHED __builtin_amdgcn_sched_barrier(0)
; template <class Epi, class Sched, bool ALIGN_EPI = false, bool SP2 = false, bool F16 = false>
; __device__ __forceinline__ void gemm_phase(PG8_LAS unsigned char* lds, const Gemm g, const Sched& S, const Epi& E) {
;     ...
;         for (int t = 0; t < nt; t += 2) {
;             const bool last = (t == nt - 2);
;             const char* a1 = cA + (size_t)(t + 1) * kstep;
;             const char* a2 = last ? nA : cA + (size_t)(t + 2) * kstep; const char* b2 = last ? nB : cB + (size_t)(t + 2) * kstep;
;             const char* a3 = a2 + kstep; const char* b3 = b2 + kstep;
;     ...
;             PG8_LDA(At, 1, 1); PG8_STAGE(PG8_SB(1, 0), b3, voffB); PG8_STAGE(PG8_SB(1, 1), b3 + hstep, voffB); PG8_STAGE(PG8_SA(1, 0), a3, voffA);
;             PG8_WAIT_V(8); PG8_WAIT_L(0); PG8_BAR; PG8_MMA(1, 0, At, B0); PG8_MMA(1, 1, At, B1); PG8_BAR; PG8_SCHED;
	s_add_i32 s16, s68, s56
	v_lshl_add_u64 v[210:211], v[210:211], 0, s[24:25]
	s_mov_b32 m0, s16
	ds_read_b128 v[178:181], v145 offset:49152
	ds_read_b128 v[182:185], v145 offset:50176
	ds_read_b128 v[186:189], v145 offset:51200
	ds_read_b128 v[190:193], v145 offset:52224
	ds_read_b128 v[194:197], v145 offset:53248
	ds_read_b128 v[198:201], v145 offset:54272
	ds_read_b128 v[202:205], v145 offset:55296
	ds_read_b128 v[206:209], v145 offset:56320
	global_load_lds_dwordx4 v[210:211], off
	s_add_i32 m0, s16, 0x2000
	s_add_u32 s14, s14, 0x160080
	v_lshl_add_u64 v[210:211], v[212:213], 0, s[24:25]
	s_addc_u32 s15, s15, 0
	s_add_i32 s16, s69, s56
	global_load_lds_dwordx4 v[210:211], off
	v_lshl_add_u64 v[210:211], s[14:15], 0, v[0:1]
	s_mov_b32 m0, s16
	s_nop 0
	global_load_lds_dwordx4 v[210:211], off
	v_lshl_add_u64 v[210:211], s[14:15], 0, v[130:131]
	s_add_i32 m0, s16, 0x2000
	s_nop 0
	global_load_lds_dwordx4 v[210:211], off
	v_lshl_add_u64 v[210:211], v[220:221], 0, s[24:25]
	s_mov_b32 m0, s61
	s_nop 0
	global_load_lds_dwordx4 v[210:211], off
	v_lshl_add_u64 v[210:211], v[222:223], 0, s[24:25]
	s_mov_b32 m0, s62
	s_nop 0
	global_load_lds_dwordx4 v[210:211], off
	s_waitcnt vmcnt(8)
	s_waitcnt lgkmcnt(0)
	s_barrier
	s_setprio 1
	s_waitcnt lgkmcnt(0)
	v_mfma_f32_16x16x32_bf16 v[62:65], v[146:149], v[178:181], v[62:65]
	v_mfma_f32_16x16x32_bf16 v[58:61], v[154:157], v[178:181], v[58:61]
	v_mfma_f32_16x16x32_bf16 v[46:49], v[146:149], v[186:189], v[46:49]
	v_mfma_f32_16x16x32_bf16 v[42:45], v[154:157], v[186:189], v[42:45]
	v_mfma_f32_16x16x32_bf16 v[30:33], v[146:149], v[194:197], v[30:33]
	v_mfma_f32_16x16x32_bf16 v[26:29], v[154:157], v[194:197], v[26:29]
	v_mfma_f32_16x16x32_bf16 v[14:17], v[146:149], v[202:205], v[14:17]
	v_mfma_f32_16x16x32_bf16 v[10:13], v[154:157], v[202:205], v[10:13]
	v_mfma_f32_16x16x32_bf16 v[62:65], v[150:153], v[182:185], v[62:65]
	v_mfma_f32_16x16x32_bf16 v[58:61], v[158:161], v[182:185], v[58:61]
	v_mfma_f32_16x16x32_bf16 v[46:49], v[150:153], v[190:193], v[46:49]
	v_mfma_f32_16x16x32_bf16 v[42:45], v[158:161], v[190:193], v[42:45]
	v_mfma_f32_16x16x32_bf16 v[30:33], v[150:153], v[198:201], v[30:33]
	v_mfma_f32_16x16x32_bf16 v[26:29], v[158:161], v[198:201], v[26:29]
	v_mfma_f32_16x16x32_bf16 v[14:17], v[150:153], v[206:209], v[14:17]
	v_mfma_f32_16x16x32_bf16 v[10:13], v[158:161], v[206:209], v[10:13]
	s_setprio 0
	s_setprio 1
	v_mfma_f32_16x16x32_bf16 v[54:57], v[162:165], v[178:181], v[54:57]
	v_mfma_f32_16x16x32_bf16 v[50:53], v[170:173], v[178:181], v[50:53]
	v_mfma_f32_16x16x32_bf16 v[38:41], v[162:165], v[186:189], v[38:41]
	v_mfma_f32_16x16x32_bf16 v[34:37], v[170:173], v[186:189], v[34:37]
	v_mfma_f32_16x16x32_bf16 v[22:25], v[162:165], v[194:197], v[22:25]
	v_mfma_f32_16x16x32_bf16 v[18:21], v[170:173], v[194:197], v[18:21]
	v_mfma_f32_16x16x32_bf16 v[6:9], v[162:165], v[202:205], v[6:9]
	v_mfma_f32_16x16x32_bf16 v[2:5], v[170:173], v[202:205], v[2:5]
	s_add_i32 s67, s67, 2
	s_add_u32 s12, s12, 0x100
	s_addc_u32 s13, s13, 0
	s_add_u32 s14, s0, s12
	s_addc_u32 s15, s1, s13
	s_add_u32 s14, s14, 0x100
	s_addc_u32 s15, s15, 0
	s_add_u32 s68, s42, s12
	s_addc_u32 s69, s43, s13
	s_add_i32 s70, 0, 0x10000
	s_cmpk_eq_i32 s12, 0x2b00
	s_cselect_b32 s17, s11, s15
	s_cselect_b32 s16, s10, s14
	s_cselect_b32 s15, s9, s69
	s_cselect_b32 s14, s8, s68
	s_add_i32 s71, 0, 0x14000
	s_cmpk_gt_u32 s67, 0x55
	v_mfma_f32_16x16x32_bf16 v[54:57], v[166:169], v[182:185], v[54:57]
	v_mfma_f32_16x16x32_bf16 v[50:53], v[174:177], v[182:185], v[50:53]
	v_mfma_f32_16x16x32_bf16 v[38:41], v[166:169], v[190:193], v[38:41]
	v_mfma_f32_16x16x32_bf16 v[34:37], v[174:177], v[190:193], v[34:37]
	v_mfma_f32_16x16x32_bf16 v[22:25], v[166:169], v[198:201], v[22:25]
	v_mfma_f32_16x16x32_bf16 v[18:21], v[174:177], v[198:201], v[18:21]
	v_mfma_f32_16x16x32_bf16 v[6:9], v[166:169], v[206:209], v[6:9]
	v_mfma_f32_16x16x32_bf16 v[2:5], v[174:177], v[206:209], v[2:5]
	s_setprio 0
	s_barrier
; #define PG8_BAR __builtin_amdgcn_s_barrier()
; template <class Epi, class Sched, bool ALIGN_EPI = false, bool SP2 = false, bool F16 = false>
; __device__ __forceinline__ void gemm_phase(PG8_LAS unsigned char* lds, const Gemm g, const Sched& S, const Epi& E) {
;     ...
;         }
;         if constexpr (ALIGN_EPI) { if (wr == 0) PG8_BAR; }
;         if constexpr (!Epi::AFTER_DRAIN) { E(acc, cur, wr, wc, fr, fq); S.done(cur); }
;         if (!has_next) break;
; #pragma unroll
;         for (int a = 0; a < 2; ++a)
; #pragma unroll
;             for (int b = 0; b < 2; ++b)
; #pragma unroll
;                 for (int m = 0; m < 4; ++m)
; #pragma unroll
;                     for (int n = 0; n < 2; ++n) acc[a][b][m][n] = (f32x4){0.f, 0.f, 0.f, 0.f};
	s_cbranch_scc0 .LBB0_2498
	s_add_u32 s12, s42, 0xffffff00
	s_addc_u32 s13, s43, -1
	s_and_b64 vcc, exec, s[40:41]
	s_cbranch_vccnz .LBB0_2485
	v_mov_b32_e32 v2, 0
	s_mov_b32 s6, s64
	s_mov_b32 s26, s65
	s_mov_b64 s[0:1], s[10:11]
	s_mov_b32 s63, s66
	v_mov_b32_e32 v3, v2
	v_mov_b32_e32 v4, v2
	v_mov_b32_e32 v5, v2
	v_mov_b32_e32 v6, v2
	v_mov_b32_e32 v7, v2
	v_mov_b32_e32 v8, v2
	v_mov_b32_e32 v9, v2
	v_mov_b32_e32 v18, v2
	v_mov_b32_e32 v19, v2
	v_mov_b32_e32 v20, v2
	v_mov_b32_e32 v21, v2
	v_mov_b32_e32 v22, v2
	v_mov_b32_e32 v23, v2
	v_mov_b32_e32 v24, v2
	v_mov_b32_e32 v25, v2
	v_mov_b32_e32 v34, v2
	v_mov_b32_e32 v35, v2
	v_mov_b32_e32 v36, v2
	v_mov_b32_e32 v37, v2
	v_mov_b32_e32 v38, v2
	v_mov_b32_e32 v39, v2
	v_mov_b32_e32 v40, v2
	v_mov_b32_e32 v41, v2
	v_mov_b32_e32 v50, v2
	v_mov_b32_e32 v51, v2
	v_mov_b32_e32 v52, v2
	v_mov_b32_e32 v53, v2
	v_mov_b32_e32 v54, v2
	v_mov_b32_e32 v55, v2
	v_mov_b32_e32 v56, v2
	v_mov_b32_e32 v57, v2
	v_mov_b32_e32 v10, v2
	v_mov_b32_e32 v11, v2
	v_mov_b32_e32 v12, v2
	v_mov_b32_e32 v13, v2
	v_mov_b32_e32 v14, v2
	v_mov_b32_e32 v15, v2
	v_mov_b32_e32 v16, v2
	v_mov_b32_e32 v17, v2
	v_mov_b32_e32 v26, v2
	v_mov_b32_e32 v27, v2
	v_mov_b32_e32 v28, v2
	v_mov_b32_e32 v29, v2
	v_mov_b32_e32 v30, v2
	v_mov_b32_e32 v31, v2
	v_mov_b32_e32 v32, v2
	v_mov_b32_e32 v33, v2
	v_mov_b32_e32 v42, v2
	v_mov_b32_e32 v43, v2
	v_mov_b32_e32 v44, v2
	v_mov_b32_e32 v45, v2
	v_mov_b32_e32 v46, v2
	v_mov_b32_e32 v47, v2
	v_mov_b32_e32 v48, v2
	v_mov_b32_e32 v49, v2
	v_mov_b32_e32 v58, v2
	v_mov_b32_e32 v59, v2
	v_mov_b32_e32 v60, v2
	v_mov_b32_e32 v61, v2
	v_mov_b32_e32 v62, v2
	v_mov_b32_e32 v63, v2
	v_mov_b32_e32 v64, v2
	v_mov_b32_e32 v65, v2
	v_mov_b32_e32 v66, v2
	v_mov_b32_e32 v67, v2
	v_mov_b32_e32 v68, v2
	v_mov_b32_e32 v69, v2
	v_mov_b32_e32 v70, v2
	v_mov_b32_e32 v71, v2
	v_mov_b32_e32 v72, v2
	v_mov_b32_e32 v73, v2
	v_mov_b32_e32 v82, v2
	v_mov_b32_e32 v83, v2
	v_mov_b32_e32 v84, v2
	v_mov_b32_e32 v85, v2
	v_mov_b32_e32 v86, v2
	v_mov_b32_e32 v87, v2
	v_mov_b32_e32 v88, v2
	v_mov_b32_e32 v89, v2
	v_mov_b32_e32 v98, v2
	v_mov_b32_e32 v99, v2
	v_mov_b32_e32 v100, v2
	v_mov_b32_e32 v101, v2
	v_mov_b32_e32 v102, v2
	v_mov_b32_e32 v103, v2
	v_mov_b32_e32 v104, v2
	v_mov_b32_e32 v105, v2
	v_mov_b32_e32 v114, v2
	v_mov_b32_e32 v115, v2
	v_mov_b32_e32 v116, v2
	v_mov_b32_e32 v117, v2
	v_mov_b32_e32 v118, v2
	v_mov_b32_e32 v119, v2
	v_mov_b32_e32 v120, v2
	v_mov_b32_e32 v121, v2
	v_mov_b32_e32 v74, v2
	v_mov_b32_e32 v75, v2
	v_mov_b32_e32 v76, v2
	v_mov_b32_e32 v77, v2
	v_mov_b32_e32 v78, v2
	v_mov_b32_e32 v79, v2
	v_mov_b32_e32 v80, v2
	v_mov_b32_e32 v81, v2
	v_mov_b32_e32 v90, v2
	v_mov_b32_e32 v91, v2
	v_mov_b32_e32 v92, v2
	v_mov_b32_e32 v93, v2
	v_mov_b32_e32 v94, v2
	v_mov_b32_e32 v95, v2
	v_mov_b32_e32 v96, v2
	v_mov_b32_e32 v97, v2
	v_mov_b32_e32 v106, v2
	v_mov_b32_e32 v107, v2
	v_mov_b32_e32 v108, v2
	v_mov_b32_e32 v109, v2
	v_mov_b32_e32 v110, v2
	v_mov_b32_e32 v111, v2
	v_mov_b32_e32 v112, v2
	v_mov_b32_e32 v113, v2
	v_mov_b32_e32 v122, v2
	v_mov_b32_e32 v123, v2
	v_mov_b32_e32 v124, v2
	v_mov_b32_e32 v125, v2
	v_mov_b32_e32 v126, v2
	v_mov_b32_e32 v127, v2
	v_mov_b32_e32 v128, v2
	v_mov_b32_e32 v129, v2
	s_andn2_b64 vcc, exec, s[38:39]
	s_cbranch_vccnz .LBB0_2486
